# adds: store-drain vmcnt(0) waits removed per tile in out0/out1/in1 GEMM sites (before K-loop, between epilogue steps); bias loads still retired by first wait of each group
# speedup vs baseline: 1.0077x; 1.0008x over previous
.LBB0_1141:
	s_add_u32 s0, s6, 0x80
	s_addc_u32 s1, s7, 0
	s_add_u32 s6, s4, 0x100
	v_mov_b32_e32 v2, 0
	s_addc_u32 s7, s5, 0
	s_mov_b32 s4, 0
	v_mov_b32_e32 v3, v2
	v_mov_b32_e32 v4, v2
	v_mov_b32_e32 v5, v2
	v_mov_b32_e32 v6, v2
	v_mov_b32_e32 v7, v2
	v_mov_b32_e32 v8, v2
	v_mov_b32_e32 v9, v2
	v_mov_b32_e32 v10, v2
	v_mov_b32_e32 v11, v2
	v_mov_b32_e32 v12, v2
	v_mov_b32_e32 v13, v2
	v_mov_b32_e32 v14, v2
	v_mov_b32_e32 v15, v2
	v_mov_b32_e32 v16, v2
	v_mov_b32_e32 v17, v2
	v_mov_b32_e32 v18, v2
	v_mov_b32_e32 v19, v2
	v_mov_b32_e32 v20, v2
	v_mov_b32_e32 v21, v2
	v_mov_b32_e32 v22, v2
	v_mov_b32_e32 v23, v2
	v_mov_b32_e32 v24, v2
	v_mov_b32_e32 v25, v2
	v_mov_b32_e32 v26, v2
	v_mov_b32_e32 v27, v2
	v_mov_b32_e32 v28, v2
	v_mov_b32_e32 v29, v2
	v_mov_b32_e32 v30, v2
	v_mov_b32_e32 v31, v2
	v_mov_b32_e32 v32, v2
	v_mov_b32_e32 v33, v2
	v_mov_b32_e32 v66, v2
	v_mov_b32_e32 v67, v2
	v_mov_b32_e32 v68, v2
	v_mov_b32_e32 v69, v2
	v_mov_b32_e32 v70, v2
	v_mov_b32_e32 v71, v2
	v_mov_b32_e32 v72, v2
	v_mov_b32_e32 v73, v2
	v_mov_b32_e32 v74, v2
	v_mov_b32_e32 v75, v2
	v_mov_b32_e32 v76, v2
	v_mov_b32_e32 v77, v2
	v_mov_b32_e32 v78, v2
	v_mov_b32_e32 v79, v2
	v_mov_b32_e32 v80, v2
	v_mov_b32_e32 v81, v2
	v_mov_b32_e32 v90, v2
	v_mov_b32_e32 v91, v2
	v_mov_b32_e32 v92, v2
	v_mov_b32_e32 v93, v2
	v_mov_b32_e32 v94, v2
	v_mov_b32_e32 v95, v2
	v_mov_b32_e32 v96, v2
	v_mov_b32_e32 v97, v2
	v_mov_b32_e32 v98, v2
	v_mov_b32_e32 v99, v2
	v_mov_b32_e32 v100, v2
	v_mov_b32_e32 v101, v2
	v_mov_b32_e32 v102, v2
	v_mov_b32_e32 v103, v2
	v_mov_b32_e32 v104, v2
	v_mov_b32_e32 v105, v2
	v_mov_b32_e32 v34, v2
	v_mov_b32_e32 v35, v2
	v_mov_b32_e32 v36, v2
	v_mov_b32_e32 v37, v2
	v_mov_b32_e32 v38, v2
	v_mov_b32_e32 v39, v2
	v_mov_b32_e32 v40, v2
	v_mov_b32_e32 v41, v2
	v_mov_b32_e32 v42, v2
	v_mov_b32_e32 v43, v2
	v_mov_b32_e32 v44, v2
	v_mov_b32_e32 v45, v2
	v_mov_b32_e32 v46, v2
	v_mov_b32_e32 v47, v2
	v_mov_b32_e32 v48, v2
	v_mov_b32_e32 v49, v2
	v_mov_b32_e32 v50, v2
	v_mov_b32_e32 v51, v2
	v_mov_b32_e32 v52, v2
	v_mov_b32_e32 v53, v2
	v_mov_b32_e32 v54, v2
	v_mov_b32_e32 v55, v2
	v_mov_b32_e32 v56, v2
	v_mov_b32_e32 v57, v2
	v_mov_b32_e32 v58, v2
	v_mov_b32_e32 v59, v2
	v_mov_b32_e32 v60, v2
	v_mov_b32_e32 v61, v2
	v_mov_b32_e32 v62, v2
	v_mov_b32_e32 v63, v2
	v_mov_b32_e32 v64, v2
	v_mov_b32_e32 v65, v2
	v_mov_b32_e32 v106, v2
	v_mov_b32_e32 v107, v2
	v_mov_b32_e32 v108, v2
	v_mov_b32_e32 v109, v2
	v_mov_b32_e32 v110, v2
	v_mov_b32_e32 v111, v2
	v_mov_b32_e32 v112, v2
	v_mov_b32_e32 v113, v2
	v_mov_b32_e32 v114, v2
	v_mov_b32_e32 v115, v2
	v_mov_b32_e32 v116, v2
	v_mov_b32_e32 v117, v2
	v_mov_b32_e32 v118, v2
	v_mov_b32_e32 v119, v2
	v_mov_b32_e32 v120, v2
	v_mov_b32_e32 v121, v2
	v_mov_b32_e32 v122, v2
	v_mov_b32_e32 v123, v2
	v_mov_b32_e32 v124, v2
	v_mov_b32_e32 v125, v2
	v_mov_b32_e32 v126, v2
	v_mov_b32_e32 v127, v2
	v_mov_b32_e32 v128, v2
	v_mov_b32_e32 v129, v2
	v_mov_b32_e32 v130, v2
	v_mov_b32_e32 v131, v2
	v_mov_b32_e32 v132, v2
	v_mov_b32_e32 v133, v2
	v_mov_b32_e32 v134, v2
	v_mov_b32_e32 v135, v2
	v_mov_b32_e32 v136, v2
	v_mov_b32_e32 v137, v2

.LBB0_1165:
	s_andn2_b64 vcc, exec, s[0:1]
	s_cbranch_vccnz .LBB0_1167
	v_pk_add_f32 v[130:131], v[126:127], v[82:83]
	v_pk_add_f32 v[132:133], v[122:123], v[86:87]
	v_mul_f32_e64 v1, |v130|, s94
	v_exp_f32_e32 v1, v1
	v_min_f32_e32 v126, 0, v130
	v_min_f32_e32 v127, 0, v131
	v_pk_add_f32 v[128:129], v[128:129], v[84:85]
	v_add_f32_e32 v1, 1.0, v1
	v_cmp_gt_f32_e32 vcc, s97, v1
	v_pk_add_f32 v[124:125], v[124:125], v[88:89]
	s_nop 0
	v_cndmask_b32_e64 v122, 0, 32, vcc
	v_ldexp_f32 v1, v1, v122
	v_log_f32_e32 v1, v1
	v_min_f32_e32 v136, 0, v124
	v_min_f32_e32 v137, 0, v125
	v_mul_f32_e32 v122, 0x3f317217, v1
	v_fma_f32 v122, v1, s28, -v122
	v_fmac_f32_e32 v122, 0x3377d1cf, v1
	v_fmac_f32_e32 v122, 0x3f317217, v1
	v_cmp_lt_f32_e64 s[0:1], |v1|, s29
	s_nop 1
	v_cndmask_b32_e64 v1, v1, v122, s[0:1]
	v_cndmask_b32_e32 v122, 0, v244, vcc
	v_sub_f32_e32 v130, v1, v122
	v_mul_f32_e64 v1, |v132|, s94
	v_exp_f32_e32 v1, v1
	v_min_f32_e32 v122, 0, v132
	v_add_f32_e32 v1, 1.0, v1
	v_cmp_gt_f32_e32 vcc, s97, v1
	s_nop 1
	v_cndmask_b32_e64 v123, 0, 32, vcc
	v_ldexp_f32 v1, v1, v123
	v_log_f32_e32 v1, v1
	s_nop 0
	v_mul_f32_e32 v123, 0x3f317217, v1
	v_fma_f32 v123, v1, s28, -v123
	v_fmac_f32_e32 v123, 0x3377d1cf, v1
	v_fmac_f32_e32 v123, 0x3f317217, v1
	v_cmp_lt_f32_e64 s[0:1], |v1|, s29
	s_nop 1
	v_cndmask_b32_e64 v1, v1, v123, s[0:1]
	v_cndmask_b32_e32 v123, 0, v244, vcc
	v_sub_f32_e32 v134, v1, v123
	v_mul_f32_e64 v1, |v131|, s94
	v_exp_f32_e32 v1, v1
	s_nop 0
	v_add_f32_e32 v1, 1.0, v1
	v_cmp_gt_f32_e32 vcc, s97, v1
	s_nop 1
	v_cndmask_b32_e64 v123, 0, 32, vcc
	v_ldexp_f32 v1, v1, v123
	v_log_f32_e32 v1, v1
	s_nop 0
	v_mul_f32_e32 v123, 0x3f317217, v1
	v_fma_f32 v123, v1, s28, -v123
	v_fmac_f32_e32 v123, 0x3377d1cf, v1
	v_fmac_f32_e32 v123, 0x3f317217, v1
	v_cmp_lt_f32_e64 s[0:1], |v1|, s29
	s_nop 1
	v_cndmask_b32_e64 v1, v1, v123, s[0:1]
	v_cndmask_b32_e32 v123, 0, v244, vcc
	v_sub_f32_e32 v131, v1, v123
	v_mul_f32_e64 v1, |v133|, s94
	v_exp_f32_e32 v1, v1
	v_min_f32_e32 v123, 0, v133
	v_min_f32_e32 v133, 0, v129
	v_pk_add_f32 v[126:127], v[126:127], v[130:131] neg_lo:[0,1] neg_hi:[0,1]
	v_add_f32_e32 v1, 1.0, v1
	v_cmp_gt_f32_e32 vcc, s97, v1
	v_pk_mul_f32 v[130:131], v[126:127], s[36:37] op_sel_hi:[1,0]
	s_nop 0
	v_cndmask_b32_e64 v132, 0, 32, vcc
	v_ldexp_f32 v1, v1, v132
	v_log_f32_e32 v1, v1
	s_nop 0
	v_mul_f32_e32 v132, 0x3f317217, v1
	v_fma_f32 v132, v1, s28, -v132
	v_fmac_f32_e32 v132, 0x3377d1cf, v1
	v_fmac_f32_e32 v132, 0x3f317217, v1
	v_cmp_lt_f32_e64 s[0:1], |v1|, s29
	s_nop 1
	v_cndmask_b32_e64 v1, v1, v132, s[0:1]
	v_cndmask_b32_e32 v132, 0, v244, vcc
	v_sub_f32_e32 v135, v1, v132
	v_mul_f32_e64 v1, |v128|, s94
	v_exp_f32_e32 v1, v1
	v_min_f32_e32 v132, 0, v128
	v_pk_add_f32 v[122:123], v[122:123], v[134:135] neg_lo:[0,1] neg_hi:[0,1]
	v_add_f32_e32 v1, 1.0, v1
	v_cmp_gt_f32_e32 vcc, s97, v1
	v_pk_mul_f32 v[134:135], v[122:123], s[36:37] op_sel_hi:[1,0]
	s_nop 0
	v_cndmask_b32_e64 v128, 0, 32, vcc
	v_ldexp_f32 v1, v1, v128
	v_log_f32_e32 v1, v1
	s_nop 0
	v_mul_f32_e32 v128, 0x3f317217, v1
	v_fma_f32 v128, v1, s28, -v128
	v_fmac_f32_e32 v128, 0x3377d1cf, v1
	v_fmac_f32_e32 v128, 0x3f317217, v1
	v_cmp_lt_f32_e64 s[0:1], |v1|, s29
	s_nop 1
	v_cndmask_b32_e64 v1, v1, v128, s[0:1]
	v_cndmask_b32_e32 v128, 0, v244, vcc
	v_sub_f32_e32 v128, v1, v128
	v_mul_f32_e64 v1, |v124|, s94
	v_exp_f32_e32 v1, v1
	s_nop 0
	v_add_f32_e32 v1, 1.0, v1
	v_cmp_gt_f32_e32 vcc, s97, v1
	s_nop 1
	v_cndmask_b32_e64 v124, 0, 32, vcc
	v_ldexp_f32 v1, v1, v124
	v_log_f32_e32 v1, v1
	s_nop 0
	v_mul_f32_e32 v124, 0x3f317217, v1
	v_fma_f32 v124, v1, s28, -v124
	v_fmac_f32_e32 v124, 0x3377d1cf, v1
	v_fmac_f32_e32 v124, 0x3f317217, v1
	v_cmp_lt_f32_e64 s[0:1], |v1|, s29
	s_nop 1
	v_cndmask_b32_e64 v1, v1, v124, s[0:1]
	v_cndmask_b32_e32 v124, 0, v244, vcc
	v_sub_f32_e32 v124, v1, v124
	v_mul_f32_e64 v1, |v129|, s94
	v_exp_f32_e32 v1, v1
	s_nop 0
	v_add_f32_e32 v1, 1.0, v1
	v_cmp_gt_f32_e32 vcc, s97, v1
	s_nop 1
	v_cndmask_b32_e64 v129, 0, 32, vcc
	v_ldexp_f32 v1, v1, v129
	v_log_f32_e32 v1, v1
	s_nop 0
	v_mul_f32_e32 v129, 0x3f317217, v1
	v_fma_f32 v129, v1, s28, -v129
	v_fmac_f32_e32 v129, 0x3377d1cf, v1
	v_fmac_f32_e32 v129, 0x3f317217, v1
	v_cmp_lt_f32_e64 s[0:1], |v1|, s29
	s_nop 1
	v_cndmask_b32_e64 v1, v1, v129, s[0:1]
	v_cndmask_b32_e32 v129, 0, v244, vcc
	v_sub_f32_e32 v129, v1, v129
	v_mul_f32_e64 v1, |v125|, s94
	v_exp_f32_e32 v1, v1
	v_pk_add_f32 v[128:129], v[132:133], v[128:129] neg_lo:[0,1] neg_hi:[0,1]
	v_add_f32_e32 v1, 1.0, v1
	v_cmp_gt_f32_e32 vcc, s97, v1
	v_pk_mul_f32 v[132:133], v[128:129], s[36:37] op_sel_hi:[1,0]
	s_nop 0
	v_cndmask_b32_e64 v125, 0, 32, vcc
	v_ldexp_f32 v1, v1, v125
	v_log_f32_e32 v1, v1
	s_nop 0
	v_mul_f32_e32 v125, 0x3f317217, v1
	v_fma_f32 v125, v1, s28, -v125
	v_fmac_f32_e32 v125, 0x3377d1cf, v1
	v_fmac_f32_e32 v125, 0x3f317217, v1
	v_cmp_lt_f32_e64 s[0:1], |v1|, s29
	s_nop 1
	v_cndmask_b32_e64 v1, v1, v125, s[0:1]
	v_cndmask_b32_e32 v125, 0, v244, vcc
	v_sub_f32_e32 v125, v1, v125
	v_pk_add_f32 v[124:125], v[136:137], v[124:125] neg_lo:[0,1] neg_hi:[0,1]
	s_nop 0
	v_pk_mul_f32 v[136:137], v[124:125], s[36:37] op_sel_hi:[1,0]

.LBB0_1171:
	s_andn2_b64 vcc, exec, s[0:1]
	s_cbranch_vccnz .LBB0_1173
	v_pk_add_f32 v[122:123], v[118:119], v[82:83]
	v_pk_add_f32 v[124:125], v[114:115], v[86:87]
	v_mul_f32_e64 v1, |v122|, s94
	v_exp_f32_e32 v1, v1
	v_min_f32_e32 v118, 0, v122
	v_min_f32_e32 v119, 0, v123
	v_pk_add_f32 v[120:121], v[120:121], v[84:85]
	v_add_f32_e32 v1, 1.0, v1
	v_cmp_gt_f32_e32 vcc, s97, v1
	v_pk_add_f32 v[116:117], v[116:117], v[88:89]
	s_nop 0
	v_cndmask_b32_e64 v114, 0, 32, vcc
	v_ldexp_f32 v1, v1, v114
	v_log_f32_e32 v1, v1
	v_min_f32_e32 v128, 0, v116
	v_min_f32_e32 v129, 0, v117
	v_mul_f32_e32 v114, 0x3f317217, v1
	v_fma_f32 v114, v1, s28, -v114
	v_fmac_f32_e32 v114, 0x3377d1cf, v1
	v_fmac_f32_e32 v114, 0x3f317217, v1
	v_cmp_lt_f32_e64 s[0:1], |v1|, s29
	s_nop 1
	v_cndmask_b32_e64 v1, v1, v114, s[0:1]
	v_cndmask_b32_e32 v114, 0, v244, vcc
	v_sub_f32_e32 v122, v1, v114
	v_mul_f32_e64 v1, |v124|, s94
	v_exp_f32_e32 v1, v1
	v_min_f32_e32 v114, 0, v124
	v_add_f32_e32 v1, 1.0, v1
	v_cmp_gt_f32_e32 vcc, s97, v1
	s_nop 1
	v_cndmask_b32_e64 v115, 0, 32, vcc
	v_ldexp_f32 v1, v1, v115
	v_log_f32_e32 v1, v1
	s_nop 0
	v_mul_f32_e32 v115, 0x3f317217, v1
	v_fma_f32 v115, v1, s28, -v115
	v_fmac_f32_e32 v115, 0x3377d1cf, v1
	v_fmac_f32_e32 v115, 0x3f317217, v1
	v_cmp_lt_f32_e64 s[0:1], |v1|, s29
	s_nop 1
	v_cndmask_b32_e64 v1, v1, v115, s[0:1]
	v_cndmask_b32_e32 v115, 0, v244, vcc
	v_sub_f32_e32 v126, v1, v115
	v_mul_f32_e64 v1, |v123|, s94
	v_exp_f32_e32 v1, v1
	s_nop 0
	v_add_f32_e32 v1, 1.0, v1
	v_cmp_gt_f32_e32 vcc, s97, v1
	s_nop 1
	v_cndmask_b32_e64 v115, 0, 32, vcc
	v_ldexp_f32 v1, v1, v115
	v_log_f32_e32 v1, v1
	s_nop 0
	v_mul_f32_e32 v115, 0x3f317217, v1
	v_fma_f32 v115, v1, s28, -v115
	v_fmac_f32_e32 v115, 0x3377d1cf, v1
	v_fmac_f32_e32 v115, 0x3f317217, v1
	v_cmp_lt_f32_e64 s[0:1], |v1|, s29
	s_nop 1
	v_cndmask_b32_e64 v1, v1, v115, s[0:1]
	v_cndmask_b32_e32 v115, 0, v244, vcc
	v_sub_f32_e32 v123, v1, v115
	v_mul_f32_e64 v1, |v125|, s94
	v_exp_f32_e32 v1, v1
	v_min_f32_e32 v115, 0, v125
	v_min_f32_e32 v125, 0, v121
	v_pk_add_f32 v[118:119], v[118:119], v[122:123] neg_lo:[0,1] neg_hi:[0,1]
	v_add_f32_e32 v1, 1.0, v1
	v_cmp_gt_f32_e32 vcc, s97, v1
	v_pk_mul_f32 v[122:123], v[118:119], s[36:37] op_sel_hi:[1,0]
	s_nop 0
	v_cndmask_b32_e64 v124, 0, 32, vcc
	v_ldexp_f32 v1, v1, v124
	v_log_f32_e32 v1, v1
	s_nop 0
	v_mul_f32_e32 v124, 0x3f317217, v1
	v_fma_f32 v124, v1, s28, -v124
	v_fmac_f32_e32 v124, 0x3377d1cf, v1
	v_fmac_f32_e32 v124, 0x3f317217, v1
	v_cmp_lt_f32_e64 s[0:1], |v1|, s29
	s_nop 1
	v_cndmask_b32_e64 v1, v1, v124, s[0:1]
	v_cndmask_b32_e32 v124, 0, v244, vcc
	v_sub_f32_e32 v127, v1, v124
	v_mul_f32_e64 v1, |v120|, s94
	v_exp_f32_e32 v1, v1
	v_min_f32_e32 v124, 0, v120
	v_pk_add_f32 v[114:115], v[114:115], v[126:127] neg_lo:[0,1] neg_hi:[0,1]
	v_add_f32_e32 v1, 1.0, v1
	v_cmp_gt_f32_e32 vcc, s97, v1
	v_pk_mul_f32 v[126:127], v[114:115], s[36:37] op_sel_hi:[1,0]
	s_nop 0
	v_cndmask_b32_e64 v120, 0, 32, vcc
	v_ldexp_f32 v1, v1, v120
	v_log_f32_e32 v1, v1
	s_nop 0
	v_mul_f32_e32 v120, 0x3f317217, v1
	v_fma_f32 v120, v1, s28, -v120
	v_fmac_f32_e32 v120, 0x3377d1cf, v1
	v_fmac_f32_e32 v120, 0x3f317217, v1
	v_cmp_lt_f32_e64 s[0:1], |v1|, s29
	s_nop 1
	v_cndmask_b32_e64 v1, v1, v120, s[0:1]
	v_cndmask_b32_e32 v120, 0, v244, vcc
	v_sub_f32_e32 v120, v1, v120
	v_mul_f32_e64 v1, |v116|, s94
	v_exp_f32_e32 v1, v1
	s_nop 0
	v_add_f32_e32 v1, 1.0, v1
	v_cmp_gt_f32_e32 vcc, s97, v1
	s_nop 1
	v_cndmask_b32_e64 v116, 0, 32, vcc
	v_ldexp_f32 v1, v1, v116
	v_log_f32_e32 v1, v1
	s_nop 0
	v_mul_f32_e32 v116, 0x3f317217, v1
	v_fma_f32 v116, v1, s28, -v116
	v_fmac_f32_e32 v116, 0x3377d1cf, v1
	v_fmac_f32_e32 v116, 0x3f317217, v1
	v_cmp_lt_f32_e64 s[0:1], |v1|, s29
	s_nop 1
	v_cndmask_b32_e64 v1, v1, v116, s[0:1]
	v_cndmask_b32_e32 v116, 0, v244, vcc
	v_sub_f32_e32 v116, v1, v116
	v_mul_f32_e64 v1, |v121|, s94
	v_exp_f32_e32 v1, v1
	s_nop 0
	v_add_f32_e32 v1, 1.0, v1
	v_cmp_gt_f32_e32 vcc, s97, v1
	s_nop 1
	v_cndmask_b32_e64 v121, 0, 32, vcc
	v_ldexp_f32 v1, v1, v121
	v_log_f32_e32 v1, v1
	s_nop 0
	v_mul_f32_e32 v121, 0x3f317217, v1
	v_fma_f32 v121, v1, s28, -v121
	v_fmac_f32_e32 v121, 0x3377d1cf, v1
	v_fmac_f32_e32 v121, 0x3f317217, v1
	v_cmp_lt_f32_e64 s[0:1], |v1|, s29
	s_nop 1
	v_cndmask_b32_e64 v1, v1, v121, s[0:1]
	v_cndmask_b32_e32 v121, 0, v244, vcc
	v_sub_f32_e32 v121, v1, v121
	v_mul_f32_e64 v1, |v117|, s94
	v_exp_f32_e32 v1, v1
	v_pk_add_f32 v[120:121], v[124:125], v[120:121] neg_lo:[0,1] neg_hi:[0,1]
	v_add_f32_e32 v1, 1.0, v1
	v_cmp_gt_f32_e32 vcc, s97, v1
	v_pk_mul_f32 v[124:125], v[120:121], s[36:37] op_sel_hi:[1,0]
	s_nop 0
	v_cndmask_b32_e64 v117, 0, 32, vcc
	v_ldexp_f32 v1, v1, v117
	v_log_f32_e32 v1, v1
	s_nop 0
	v_mul_f32_e32 v117, 0x3f317217, v1
	v_fma_f32 v117, v1, s28, -v117
	v_fmac_f32_e32 v117, 0x3377d1cf, v1
	v_fmac_f32_e32 v117, 0x3f317217, v1
	v_cmp_lt_f32_e64 s[0:1], |v1|, s29
	s_nop 1
	v_cndmask_b32_e64 v1, v1, v117, s[0:1]
	v_cndmask_b32_e32 v117, 0, v244, vcc
	v_sub_f32_e32 v117, v1, v117
	v_pk_add_f32 v[116:117], v[128:129], v[116:117] neg_lo:[0,1] neg_hi:[0,1]
	s_nop 0
	v_pk_mul_f32 v[128:129], v[116:117], s[36:37] op_sel_hi:[1,0]

.LBB0_1177:
	s_andn2_b64 vcc, exec, s[0:1]
	s_cbranch_vccnz .LBB0_1179
	v_pk_add_f32 v[114:115], v[110:111], v[82:83]
	v_pk_add_f32 v[116:117], v[106:107], v[86:87]
	v_mul_f32_e64 v1, |v114|, s94
	v_exp_f32_e32 v1, v1
	v_min_f32_e32 v110, 0, v114
	v_min_f32_e32 v111, 0, v115
	v_pk_add_f32 v[112:113], v[112:113], v[84:85]
	v_add_f32_e32 v1, 1.0, v1
	v_cmp_gt_f32_e32 vcc, s97, v1
	v_pk_add_f32 v[108:109], v[108:109], v[88:89]
	s_nop 0
	v_cndmask_b32_e64 v106, 0, 32, vcc
	v_ldexp_f32 v1, v1, v106
	v_log_f32_e32 v1, v1
	v_min_f32_e32 v120, 0, v108
	v_min_f32_e32 v121, 0, v109
	v_mul_f32_e32 v106, 0x3f317217, v1
	v_fma_f32 v106, v1, s28, -v106
	v_fmac_f32_e32 v106, 0x3377d1cf, v1
	v_fmac_f32_e32 v106, 0x3f317217, v1
	v_cmp_lt_f32_e64 s[0:1], |v1|, s29
	s_nop 1
	v_cndmask_b32_e64 v1, v1, v106, s[0:1]
	v_cndmask_b32_e32 v106, 0, v244, vcc
	v_sub_f32_e32 v114, v1, v106
	v_mul_f32_e64 v1, |v116|, s94
	v_exp_f32_e32 v1, v1
	v_min_f32_e32 v106, 0, v116
	v_add_f32_e32 v1, 1.0, v1
	v_cmp_gt_f32_e32 vcc, s97, v1
	s_nop 1
	v_cndmask_b32_e64 v107, 0, 32, vcc
	v_ldexp_f32 v1, v1, v107
	v_log_f32_e32 v1, v1
	s_nop 0
	v_mul_f32_e32 v107, 0x3f317217, v1
	v_fma_f32 v107, v1, s28, -v107
	v_fmac_f32_e32 v107, 0x3377d1cf, v1
	v_fmac_f32_e32 v107, 0x3f317217, v1
	v_cmp_lt_f32_e64 s[0:1], |v1|, s29
	s_nop 1
	v_cndmask_b32_e64 v1, v1, v107, s[0:1]
	v_cndmask_b32_e32 v107, 0, v244, vcc
	v_sub_f32_e32 v118, v1, v107
	v_mul_f32_e64 v1, |v115|, s94
	v_exp_f32_e32 v1, v1
	s_nop 0
	v_add_f32_e32 v1, 1.0, v1
	v_cmp_gt_f32_e32 vcc, s97, v1
	s_nop 1
	v_cndmask_b32_e64 v107, 0, 32, vcc
	v_ldexp_f32 v1, v1, v107
	v_log_f32_e32 v1, v1
	s_nop 0
	v_mul_f32_e32 v107, 0x3f317217, v1
	v_fma_f32 v107, v1, s28, -v107
	v_fmac_f32_e32 v107, 0x3377d1cf, v1
	v_fmac_f32_e32 v107, 0x3f317217, v1
	v_cmp_lt_f32_e64 s[0:1], |v1|, s29
	s_nop 1
	v_cndmask_b32_e64 v1, v1, v107, s[0:1]
	v_cndmask_b32_e32 v107, 0, v244, vcc
	v_sub_f32_e32 v115, v1, v107
	v_mul_f32_e64 v1, |v117|, s94
	v_exp_f32_e32 v1, v1
	v_min_f32_e32 v107, 0, v117
	v_min_f32_e32 v117, 0, v113
	v_pk_add_f32 v[110:111], v[110:111], v[114:115] neg_lo:[0,1] neg_hi:[0,1]
	v_add_f32_e32 v1, 1.0, v1
	v_cmp_gt_f32_e32 vcc, s97, v1
	v_pk_mul_f32 v[114:115], v[110:111], s[36:37] op_sel_hi:[1,0]
	s_nop 0
	v_cndmask_b32_e64 v116, 0, 32, vcc
	v_ldexp_f32 v1, v1, v116
	v_log_f32_e32 v1, v1
	s_nop 0
	v_mul_f32_e32 v116, 0x3f317217, v1
	v_fma_f32 v116, v1, s28, -v116
	v_fmac_f32_e32 v116, 0x3377d1cf, v1
	v_fmac_f32_e32 v116, 0x3f317217, v1
	v_cmp_lt_f32_e64 s[0:1], |v1|, s29
	s_nop 1
	v_cndmask_b32_e64 v1, v1, v116, s[0:1]
	v_cndmask_b32_e32 v116, 0, v244, vcc
	v_sub_f32_e32 v119, v1, v116
	v_mul_f32_e64 v1, |v112|, s94
	v_exp_f32_e32 v1, v1
	v_min_f32_e32 v116, 0, v112
	v_pk_add_f32 v[106:107], v[106:107], v[118:119] neg_lo:[0,1] neg_hi:[0,1]
	v_add_f32_e32 v1, 1.0, v1
	v_cmp_gt_f32_e32 vcc, s97, v1
	v_pk_mul_f32 v[118:119], v[106:107], s[36:37] op_sel_hi:[1,0]
	s_nop 0
	v_cndmask_b32_e64 v112, 0, 32, vcc
	v_ldexp_f32 v1, v1, v112
	v_log_f32_e32 v1, v1
	s_nop 0
	v_mul_f32_e32 v112, 0x3f317217, v1
	v_fma_f32 v112, v1, s28, -v112
	v_fmac_f32_e32 v112, 0x3377d1cf, v1
	v_fmac_f32_e32 v112, 0x3f317217, v1
	v_cmp_lt_f32_e64 s[0:1], |v1|, s29
	s_nop 1
	v_cndmask_b32_e64 v1, v1, v112, s[0:1]
	v_cndmask_b32_e32 v112, 0, v244, vcc
	v_sub_f32_e32 v112, v1, v112
	v_mul_f32_e64 v1, |v108|, s94
	v_exp_f32_e32 v1, v1
	s_nop 0
	v_add_f32_e32 v1, 1.0, v1
	v_cmp_gt_f32_e32 vcc, s97, v1
	s_nop 1
	v_cndmask_b32_e64 v108, 0, 32, vcc
	v_ldexp_f32 v1, v1, v108
	v_log_f32_e32 v1, v1
	s_nop 0
	v_mul_f32_e32 v108, 0x3f317217, v1
	v_fma_f32 v108, v1, s28, -v108
	v_fmac_f32_e32 v108, 0x3377d1cf, v1
	v_fmac_f32_e32 v108, 0x3f317217, v1
	v_cmp_lt_f32_e64 s[0:1], |v1|, s29
	s_nop 1
	v_cndmask_b32_e64 v1, v1, v108, s[0:1]
	v_cndmask_b32_e32 v108, 0, v244, vcc
	v_sub_f32_e32 v108, v1, v108
	v_mul_f32_e64 v1, |v113|, s94
	v_exp_f32_e32 v1, v1
	s_nop 0
	v_add_f32_e32 v1, 1.0, v1
	v_cmp_gt_f32_e32 vcc, s97, v1
	s_nop 1
	v_cndmask_b32_e64 v113, 0, 32, vcc
	v_ldexp_f32 v1, v1, v113
	v_log_f32_e32 v1, v1
	s_nop 0
	v_mul_f32_e32 v113, 0x3f317217, v1
	v_fma_f32 v113, v1, s28, -v113
	v_fmac_f32_e32 v113, 0x3377d1cf, v1
	v_fmac_f32_e32 v113, 0x3f317217, v1
	v_cmp_lt_f32_e64 s[0:1], |v1|, s29
	s_nop 1
	v_cndmask_b32_e64 v1, v1, v113, s[0:1]
	v_cndmask_b32_e32 v113, 0, v244, vcc
	v_sub_f32_e32 v113, v1, v113
	v_mul_f32_e64 v1, |v109|, s94
	v_exp_f32_e32 v1, v1
	v_pk_add_f32 v[112:113], v[116:117], v[112:113] neg_lo:[0,1] neg_hi:[0,1]
	v_add_f32_e32 v1, 1.0, v1
	v_cmp_gt_f32_e32 vcc, s97, v1
	v_pk_mul_f32 v[116:117], v[112:113], s[36:37] op_sel_hi:[1,0]
	s_nop 0
	v_cndmask_b32_e64 v109, 0, 32, vcc
	v_ldexp_f32 v1, v1, v109
	v_log_f32_e32 v1, v1
	s_nop 0
	v_mul_f32_e32 v109, 0x3f317217, v1
	v_fma_f32 v109, v1, s28, -v109
	v_fmac_f32_e32 v109, 0x3377d1cf, v1
	v_fmac_f32_e32 v109, 0x3f317217, v1
	v_cmp_lt_f32_e64 s[0:1], |v1|, s29
	s_nop 1
	v_cndmask_b32_e64 v1, v1, v109, s[0:1]
	v_cndmask_b32_e32 v109, 0, v244, vcc
	v_sub_f32_e32 v109, v1, v109
	v_pk_add_f32 v[108:109], v[120:121], v[108:109] neg_lo:[0,1] neg_hi:[0,1]
	s_nop 0
	v_pk_mul_f32 v[120:121], v[108:109], s[36:37] op_sel_hi:[1,0]

.LBB0_1183:
	s_andn2_b64 vcc, exec, s[0:1]
	s_cbranch_vccnz .LBB0_1185
	v_pk_add_f32 v[106:107], v[102:103], v[82:83]
	v_pk_add_f32 v[108:109], v[98:99], v[86:87]
	v_mul_f32_e64 v1, |v106|, s94
	v_exp_f32_e32 v1, v1
	v_min_f32_e32 v102, 0, v106
	v_min_f32_e32 v103, 0, v107
	v_pk_add_f32 v[104:105], v[104:105], v[84:85]
	v_add_f32_e32 v1, 1.0, v1
	v_cmp_gt_f32_e32 vcc, s97, v1
	v_pk_add_f32 v[100:101], v[100:101], v[88:89]
	s_nop 0
	v_cndmask_b32_e64 v98, 0, 32, vcc
	v_ldexp_f32 v1, v1, v98
	v_log_f32_e32 v1, v1
	v_min_f32_e32 v112, 0, v100
	v_min_f32_e32 v113, 0, v101
	v_mul_f32_e32 v98, 0x3f317217, v1
	v_fma_f32 v98, v1, s28, -v98
	v_fmac_f32_e32 v98, 0x3377d1cf, v1
	v_fmac_f32_e32 v98, 0x3f317217, v1
	v_cmp_lt_f32_e64 s[0:1], |v1|, s29
	s_nop 1
	v_cndmask_b32_e64 v1, v1, v98, s[0:1]
	v_cndmask_b32_e32 v98, 0, v244, vcc
	v_sub_f32_e32 v106, v1, v98
	v_mul_f32_e64 v1, |v108|, s94
	v_exp_f32_e32 v1, v1
	v_min_f32_e32 v98, 0, v108
	v_add_f32_e32 v1, 1.0, v1
	v_cmp_gt_f32_e32 vcc, s97, v1
	s_nop 1
	v_cndmask_b32_e64 v99, 0, 32, vcc
	v_ldexp_f32 v1, v1, v99
	v_log_f32_e32 v1, v1
	s_nop 0
	v_mul_f32_e32 v99, 0x3f317217, v1
	v_fma_f32 v99, v1, s28, -v99
	v_fmac_f32_e32 v99, 0x3377d1cf, v1
	v_fmac_f32_e32 v99, 0x3f317217, v1
	v_cmp_lt_f32_e64 s[0:1], |v1|, s29
	s_nop 1
	v_cndmask_b32_e64 v1, v1, v99, s[0:1]
	v_cndmask_b32_e32 v99, 0, v244, vcc
	v_sub_f32_e32 v110, v1, v99
	v_mul_f32_e64 v1, |v107|, s94
	v_exp_f32_e32 v1, v1
	s_nop 0
	v_add_f32_e32 v1, 1.0, v1
	v_cmp_gt_f32_e32 vcc, s97, v1
	s_nop 1
	v_cndmask_b32_e64 v99, 0, 32, vcc
	v_ldexp_f32 v1, v1, v99
	v_log_f32_e32 v1, v1
	s_nop 0
	v_mul_f32_e32 v99, 0x3f317217, v1
	v_fma_f32 v99, v1, s28, -v99
	v_fmac_f32_e32 v99, 0x3377d1cf, v1
	v_fmac_f32_e32 v99, 0x3f317217, v1
	v_cmp_lt_f32_e64 s[0:1], |v1|, s29
	s_nop 1
	v_cndmask_b32_e64 v1, v1, v99, s[0:1]
	v_cndmask_b32_e32 v99, 0, v244, vcc
	v_sub_f32_e32 v107, v1, v99
	v_mul_f32_e64 v1, |v109|, s94
	v_exp_f32_e32 v1, v1
	v_min_f32_e32 v99, 0, v109
	v_min_f32_e32 v109, 0, v105
	v_pk_add_f32 v[102:103], v[102:103], v[106:107] neg_lo:[0,1] neg_hi:[0,1]
	v_add_f32_e32 v1, 1.0, v1
	v_cmp_gt_f32_e32 vcc, s97, v1
	v_pk_mul_f32 v[106:107], v[102:103], s[36:37] op_sel_hi:[1,0]
	s_nop 0
	v_cndmask_b32_e64 v108, 0, 32, vcc
	v_ldexp_f32 v1, v1, v108
	v_log_f32_e32 v1, v1
	s_nop 0
	v_mul_f32_e32 v108, 0x3f317217, v1
	v_fma_f32 v108, v1, s28, -v108
	v_fmac_f32_e32 v108, 0x3377d1cf, v1
	v_fmac_f32_e32 v108, 0x3f317217, v1
	v_cmp_lt_f32_e64 s[0:1], |v1|, s29
	s_nop 1
	v_cndmask_b32_e64 v1, v1, v108, s[0:1]
	v_cndmask_b32_e32 v108, 0, v244, vcc
	v_sub_f32_e32 v111, v1, v108
	v_mul_f32_e64 v1, |v104|, s94
	v_exp_f32_e32 v1, v1
	v_min_f32_e32 v108, 0, v104
	v_pk_add_f32 v[98:99], v[98:99], v[110:111] neg_lo:[0,1] neg_hi:[0,1]
	v_add_f32_e32 v1, 1.0, v1
	v_cmp_gt_f32_e32 vcc, s97, v1
	v_pk_mul_f32 v[110:111], v[98:99], s[36:37] op_sel_hi:[1,0]
	s_nop 0
	v_cndmask_b32_e64 v104, 0, 32, vcc
	v_ldexp_f32 v1, v1, v104
	v_log_f32_e32 v1, v1
	s_nop 0
	v_mul_f32_e32 v104, 0x3f317217, v1
	v_fma_f32 v104, v1, s28, -v104
	v_fmac_f32_e32 v104, 0x3377d1cf, v1
	v_fmac_f32_e32 v104, 0x3f317217, v1
	v_cmp_lt_f32_e64 s[0:1], |v1|, s29
	s_nop 1
	v_cndmask_b32_e64 v1, v1, v104, s[0:1]
	v_cndmask_b32_e32 v104, 0, v244, vcc
	v_sub_f32_e32 v104, v1, v104
	v_mul_f32_e64 v1, |v100|, s94
	v_exp_f32_e32 v1, v1
	s_nop 0
	v_add_f32_e32 v1, 1.0, v1
	v_cmp_gt_f32_e32 vcc, s97, v1
	s_nop 1
	v_cndmask_b32_e64 v100, 0, 32, vcc
	v_ldexp_f32 v1, v1, v100
	v_log_f32_e32 v1, v1
	s_nop 0
	v_mul_f32_e32 v100, 0x3f317217, v1
	v_fma_f32 v100, v1, s28, -v100
	v_fmac_f32_e32 v100, 0x3377d1cf, v1
	v_fmac_f32_e32 v100, 0x3f317217, v1
	v_cmp_lt_f32_e64 s[0:1], |v1|, s29
	s_nop 1
	v_cndmask_b32_e64 v1, v1, v100, s[0:1]
	v_cndmask_b32_e32 v100, 0, v244, vcc
	v_sub_f32_e32 v100, v1, v100
	v_mul_f32_e64 v1, |v105|, s94
	v_exp_f32_e32 v1, v1
	s_nop 0
	v_add_f32_e32 v1, 1.0, v1
	v_cmp_gt_f32_e32 vcc, s97, v1
	s_nop 1
	v_cndmask_b32_e64 v105, 0, 32, vcc
	v_ldexp_f32 v1, v1, v105
	v_log_f32_e32 v1, v1
	s_nop 0
	v_mul_f32_e32 v105, 0x3f317217, v1
	v_fma_f32 v105, v1, s28, -v105
	v_fmac_f32_e32 v105, 0x3377d1cf, v1
	v_fmac_f32_e32 v105, 0x3f317217, v1
	v_cmp_lt_f32_e64 s[0:1], |v1|, s29
	s_nop 1
	v_cndmask_b32_e64 v1, v1, v105, s[0:1]
	v_cndmask_b32_e32 v105, 0, v244, vcc
	v_sub_f32_e32 v105, v1, v105
	v_mul_f32_e64 v1, |v101|, s94
	v_exp_f32_e32 v1, v1
	v_pk_add_f32 v[104:105], v[108:109], v[104:105] neg_lo:[0,1] neg_hi:[0,1]
	v_add_f32_e32 v1, 1.0, v1
	v_cmp_gt_f32_e32 vcc, s97, v1
	v_pk_mul_f32 v[108:109], v[104:105], s[36:37] op_sel_hi:[1,0]
	s_nop 0
	v_cndmask_b32_e64 v101, 0, 32, vcc
	v_ldexp_f32 v1, v1, v101
	v_log_f32_e32 v1, v1
	s_nop 0
	v_mul_f32_e32 v101, 0x3f317217, v1
	v_fma_f32 v101, v1, s28, -v101
	v_fmac_f32_e32 v101, 0x3377d1cf, v1
	v_fmac_f32_e32 v101, 0x3f317217, v1
	v_cmp_lt_f32_e64 s[0:1], |v1|, s29
	s_nop 1
	v_cndmask_b32_e64 v1, v1, v101, s[0:1]
	v_cndmask_b32_e32 v101, 0, v244, vcc
	v_sub_f32_e32 v101, v1, v101
	v_pk_add_f32 v[100:101], v[112:113], v[100:101] neg_lo:[0,1] neg_hi:[0,1]
	s_nop 0
	v_pk_mul_f32 v[112:113], v[100:101], s[36:37] op_sel_hi:[1,0]

.LBB0_1189:
	s_andn2_b64 vcc, exec, s[0:1]
	s_cbranch_vccnz .LBB0_1191
	v_pk_add_f32 v[98:99], v[94:95], v[82:83]
	v_pk_add_f32 v[100:101], v[90:91], v[86:87]
	v_mul_f32_e64 v1, |v98|, s94
	v_exp_f32_e32 v1, v1
	v_min_f32_e32 v94, 0, v98
	v_min_f32_e32 v95, 0, v99
	v_pk_add_f32 v[96:97], v[96:97], v[84:85]
	v_add_f32_e32 v1, 1.0, v1
	v_cmp_gt_f32_e32 vcc, s97, v1
	v_pk_add_f32 v[92:93], v[92:93], v[88:89]
	s_nop 0
	v_cndmask_b32_e64 v90, 0, 32, vcc
	v_ldexp_f32 v1, v1, v90
	v_log_f32_e32 v1, v1
	v_min_f32_e32 v104, 0, v92
	v_min_f32_e32 v105, 0, v93
	v_mul_f32_e32 v90, 0x3f317217, v1
	v_fma_f32 v90, v1, s28, -v90
	v_fmac_f32_e32 v90, 0x3377d1cf, v1
	v_fmac_f32_e32 v90, 0x3f317217, v1
	v_cmp_lt_f32_e64 s[0:1], |v1|, s29
	s_nop 1
	v_cndmask_b32_e64 v1, v1, v90, s[0:1]
	v_cndmask_b32_e32 v90, 0, v244, vcc
	v_sub_f32_e32 v98, v1, v90
	v_mul_f32_e64 v1, |v100|, s94
	v_exp_f32_e32 v1, v1
	v_min_f32_e32 v90, 0, v100
	v_add_f32_e32 v1, 1.0, v1
	v_cmp_gt_f32_e32 vcc, s97, v1
	s_nop 1
	v_cndmask_b32_e64 v91, 0, 32, vcc
	v_ldexp_f32 v1, v1, v91
	v_log_f32_e32 v1, v1
	s_nop 0
	v_mul_f32_e32 v91, 0x3f317217, v1
	v_fma_f32 v91, v1, s28, -v91
	v_fmac_f32_e32 v91, 0x3377d1cf, v1
	v_fmac_f32_e32 v91, 0x3f317217, v1
	v_cmp_lt_f32_e64 s[0:1], |v1|, s29
	s_nop 1
	v_cndmask_b32_e64 v1, v1, v91, s[0:1]
	v_cndmask_b32_e32 v91, 0, v244, vcc
	v_sub_f32_e32 v102, v1, v91
	v_mul_f32_e64 v1, |v99|, s94
	v_exp_f32_e32 v1, v1
	s_nop 0
	v_add_f32_e32 v1, 1.0, v1
	v_cmp_gt_f32_e32 vcc, s97, v1
	s_nop 1
	v_cndmask_b32_e64 v91, 0, 32, vcc
	v_ldexp_f32 v1, v1, v91
	v_log_f32_e32 v1, v1
	s_nop 0
	v_mul_f32_e32 v91, 0x3f317217, v1
	v_fma_f32 v91, v1, s28, -v91
	v_fmac_f32_e32 v91, 0x3377d1cf, v1
	v_fmac_f32_e32 v91, 0x3f317217, v1
	v_cmp_lt_f32_e64 s[0:1], |v1|, s29
	s_nop 1
	v_cndmask_b32_e64 v1, v1, v91, s[0:1]
	v_cndmask_b32_e32 v91, 0, v244, vcc
	v_sub_f32_e32 v99, v1, v91
	v_mul_f32_e64 v1, |v101|, s94
	v_exp_f32_e32 v1, v1
	v_min_f32_e32 v91, 0, v101
	v_min_f32_e32 v101, 0, v97
	v_pk_add_f32 v[94:95], v[94:95], v[98:99] neg_lo:[0,1] neg_hi:[0,1]
	v_add_f32_e32 v1, 1.0, v1
	v_cmp_gt_f32_e32 vcc, s97, v1
	v_pk_mul_f32 v[98:99], v[94:95], s[36:37] op_sel_hi:[1,0]
	s_nop 0
	v_cndmask_b32_e64 v100, 0, 32, vcc
	v_ldexp_f32 v1, v1, v100
	v_log_f32_e32 v1, v1
	s_nop 0
	v_mul_f32_e32 v100, 0x3f317217, v1
	v_fma_f32 v100, v1, s28, -v100
	v_fmac_f32_e32 v100, 0x3377d1cf, v1
	v_fmac_f32_e32 v100, 0x3f317217, v1
	v_cmp_lt_f32_e64 s[0:1], |v1|, s29
	s_nop 1
	v_cndmask_b32_e64 v1, v1, v100, s[0:1]
	v_cndmask_b32_e32 v100, 0, v244, vcc
	v_sub_f32_e32 v103, v1, v100
	v_mul_f32_e64 v1, |v96|, s94
	v_exp_f32_e32 v1, v1
	v_min_f32_e32 v100, 0, v96
	v_pk_add_f32 v[90:91], v[90:91], v[102:103] neg_lo:[0,1] neg_hi:[0,1]
	v_add_f32_e32 v1, 1.0, v1
	v_cmp_gt_f32_e32 vcc, s97, v1
	v_pk_mul_f32 v[102:103], v[90:91], s[36:37] op_sel_hi:[1,0]
	s_nop 0
	v_cndmask_b32_e64 v96, 0, 32, vcc
	v_ldexp_f32 v1, v1, v96
	v_log_f32_e32 v1, v1
	s_nop 0
	v_mul_f32_e32 v96, 0x3f317217, v1
	v_fma_f32 v96, v1, s28, -v96
	v_fmac_f32_e32 v96, 0x3377d1cf, v1
	v_fmac_f32_e32 v96, 0x3f317217, v1
	v_cmp_lt_f32_e64 s[0:1], |v1|, s29
	s_nop 1
	v_cndmask_b32_e64 v1, v1, v96, s[0:1]
	v_cndmask_b32_e32 v96, 0, v244, vcc
	v_sub_f32_e32 v96, v1, v96
	v_mul_f32_e64 v1, |v92|, s94
	v_exp_f32_e32 v1, v1
	s_nop 0
	v_add_f32_e32 v1, 1.0, v1
	v_cmp_gt_f32_e32 vcc, s97, v1
	s_nop 1
	v_cndmask_b32_e64 v92, 0, 32, vcc
	v_ldexp_f32 v1, v1, v92
	v_log_f32_e32 v1, v1
	s_nop 0
	v_mul_f32_e32 v92, 0x3f317217, v1
	v_fma_f32 v92, v1, s28, -v92
	v_fmac_f32_e32 v92, 0x3377d1cf, v1
	v_fmac_f32_e32 v92, 0x3f317217, v1
	v_cmp_lt_f32_e64 s[0:1], |v1|, s29
	s_nop 1
	v_cndmask_b32_e64 v1, v1, v92, s[0:1]
	v_cndmask_b32_e32 v92, 0, v244, vcc
	v_sub_f32_e32 v92, v1, v92
	v_mul_f32_e64 v1, |v97|, s94
	v_exp_f32_e32 v1, v1
	s_nop 0
	v_add_f32_e32 v1, 1.0, v1
	v_cmp_gt_f32_e32 vcc, s97, v1
	s_nop 1
	v_cndmask_b32_e64 v97, 0, 32, vcc
	v_ldexp_f32 v1, v1, v97
	v_log_f32_e32 v1, v1
	s_nop 0
	v_mul_f32_e32 v97, 0x3f317217, v1
	v_fma_f32 v97, v1, s28, -v97
	v_fmac_f32_e32 v97, 0x3377d1cf, v1
	v_fmac_f32_e32 v97, 0x3f317217, v1
	v_cmp_lt_f32_e64 s[0:1], |v1|, s29
	s_nop 1
	v_cndmask_b32_e64 v1, v1, v97, s[0:1]
	v_cndmask_b32_e32 v97, 0, v244, vcc
	v_sub_f32_e32 v97, v1, v97
	v_mul_f32_e64 v1, |v93|, s94
	v_exp_f32_e32 v1, v1
	v_pk_add_f32 v[96:97], v[100:101], v[96:97] neg_lo:[0,1] neg_hi:[0,1]
	v_add_f32_e32 v1, 1.0, v1
	v_cmp_gt_f32_e32 vcc, s97, v1
	v_pk_mul_f32 v[100:101], v[96:97], s[36:37] op_sel_hi:[1,0]
	s_nop 0
	v_cndmask_b32_e64 v93, 0, 32, vcc
	v_ldexp_f32 v1, v1, v93
	v_log_f32_e32 v1, v1
	s_nop 0
	v_mul_f32_e32 v93, 0x3f317217, v1
	v_fma_f32 v93, v1, s28, -v93
	v_fmac_f32_e32 v93, 0x3377d1cf, v1
	v_fmac_f32_e32 v93, 0x3f317217, v1
	v_cmp_lt_f32_e64 s[0:1], |v1|, s29
	s_nop 1
	v_cndmask_b32_e64 v1, v1, v93, s[0:1]
	v_cndmask_b32_e32 v93, 0, v244, vcc
	v_sub_f32_e32 v93, v1, v93
	v_pk_add_f32 v[92:93], v[104:105], v[92:93] neg_lo:[0,1] neg_hi:[0,1]
	s_nop 0
	v_pk_mul_f32 v[104:105], v[92:93], s[36:37] op_sel_hi:[1,0]

.LBB0_1195:
	s_andn2_b64 vcc, exec, s[0:1]
	s_cbranch_vccnz .LBB0_1197
	v_pk_add_f32 v[90:91], v[78:79], v[82:83]
	v_pk_add_f32 v[92:93], v[74:75], v[86:87]
	v_mul_f32_e64 v1, |v90|, s94
	v_exp_f32_e32 v1, v1
	v_min_f32_e32 v78, 0, v90
	v_min_f32_e32 v79, 0, v91
	v_pk_add_f32 v[80:81], v[80:81], v[84:85]
	v_add_f32_e32 v1, 1.0, v1
	v_cmp_gt_f32_e32 vcc, s97, v1
	v_pk_add_f32 v[76:77], v[76:77], v[88:89]
	s_nop 0
	v_cndmask_b32_e64 v74, 0, 32, vcc
	v_ldexp_f32 v1, v1, v74
	v_log_f32_e32 v1, v1
	v_min_f32_e32 v96, 0, v76
	v_min_f32_e32 v97, 0, v77
	v_mul_f32_e32 v74, 0x3f317217, v1
	v_fma_f32 v74, v1, s28, -v74
	v_fmac_f32_e32 v74, 0x3377d1cf, v1
	v_fmac_f32_e32 v74, 0x3f317217, v1
	v_cmp_lt_f32_e64 s[0:1], |v1|, s29
	s_nop 1
	v_cndmask_b32_e64 v1, v1, v74, s[0:1]
	v_cndmask_b32_e32 v74, 0, v244, vcc
	v_sub_f32_e32 v90, v1, v74
	v_mul_f32_e64 v1, |v92|, s94
	v_exp_f32_e32 v1, v1
	v_min_f32_e32 v74, 0, v92
	v_add_f32_e32 v1, 1.0, v1
	v_cmp_gt_f32_e32 vcc, s97, v1
	s_nop 1
	v_cndmask_b32_e64 v75, 0, 32, vcc
	v_ldexp_f32 v1, v1, v75
	v_log_f32_e32 v1, v1
	s_nop 0
	v_mul_f32_e32 v75, 0x3f317217, v1
	v_fma_f32 v75, v1, s28, -v75
	v_fmac_f32_e32 v75, 0x3377d1cf, v1
	v_fmac_f32_e32 v75, 0x3f317217, v1
	v_cmp_lt_f32_e64 s[0:1], |v1|, s29
	s_nop 1
	v_cndmask_b32_e64 v1, v1, v75, s[0:1]
	v_cndmask_b32_e32 v75, 0, v244, vcc
	v_sub_f32_e32 v94, v1, v75
	v_mul_f32_e64 v1, |v91|, s94
	v_exp_f32_e32 v1, v1
	s_nop 0
	v_add_f32_e32 v1, 1.0, v1
	v_cmp_gt_f32_e32 vcc, s97, v1
	s_nop 1
	v_cndmask_b32_e64 v75, 0, 32, vcc
	v_ldexp_f32 v1, v1, v75
	v_log_f32_e32 v1, v1
	s_nop 0
	v_mul_f32_e32 v75, 0x3f317217, v1
	v_fma_f32 v75, v1, s28, -v75
	v_fmac_f32_e32 v75, 0x3377d1cf, v1
	v_fmac_f32_e32 v75, 0x3f317217, v1
	v_cmp_lt_f32_e64 s[0:1], |v1|, s29
	s_nop 1
	v_cndmask_b32_e64 v1, v1, v75, s[0:1]
	v_cndmask_b32_e32 v75, 0, v244, vcc
	v_sub_f32_e32 v91, v1, v75
	v_mul_f32_e64 v1, |v93|, s94
	v_exp_f32_e32 v1, v1
	v_min_f32_e32 v75, 0, v93
	v_min_f32_e32 v93, 0, v81
	v_pk_add_f32 v[78:79], v[78:79], v[90:91] neg_lo:[0,1] neg_hi:[0,1]
	v_add_f32_e32 v1, 1.0, v1
	v_cmp_gt_f32_e32 vcc, s97, v1
	v_pk_mul_f32 v[90:91], v[78:79], s[36:37] op_sel_hi:[1,0]
	s_nop 0
	v_cndmask_b32_e64 v92, 0, 32, vcc
	v_ldexp_f32 v1, v1, v92
	v_log_f32_e32 v1, v1
	s_nop 0
	v_mul_f32_e32 v92, 0x3f317217, v1
	v_fma_f32 v92, v1, s28, -v92
	v_fmac_f32_e32 v92, 0x3377d1cf, v1
	v_fmac_f32_e32 v92, 0x3f317217, v1
	v_cmp_lt_f32_e64 s[0:1], |v1|, s29
	s_nop 1
	v_cndmask_b32_e64 v1, v1, v92, s[0:1]
	v_cndmask_b32_e32 v92, 0, v244, vcc
	v_sub_f32_e32 v95, v1, v92
	v_mul_f32_e64 v1, |v80|, s94
	v_exp_f32_e32 v1, v1
	v_min_f32_e32 v92, 0, v80
	v_pk_add_f32 v[74:75], v[74:75], v[94:95] neg_lo:[0,1] neg_hi:[0,1]
	v_add_f32_e32 v1, 1.0, v1
	v_cmp_gt_f32_e32 vcc, s97, v1
	v_pk_mul_f32 v[94:95], v[74:75], s[36:37] op_sel_hi:[1,0]
	s_nop 0
	v_cndmask_b32_e64 v80, 0, 32, vcc
	v_ldexp_f32 v1, v1, v80
	v_log_f32_e32 v1, v1
	s_nop 0
	v_mul_f32_e32 v80, 0x3f317217, v1
	v_fma_f32 v80, v1, s28, -v80
	v_fmac_f32_e32 v80, 0x3377d1cf, v1
	v_fmac_f32_e32 v80, 0x3f317217, v1
	v_cmp_lt_f32_e64 s[0:1], |v1|, s29
	s_nop 1
	v_cndmask_b32_e64 v1, v1, v80, s[0:1]
	v_cndmask_b32_e32 v80, 0, v244, vcc
	v_sub_f32_e32 v80, v1, v80
	v_mul_f32_e64 v1, |v76|, s94
	v_exp_f32_e32 v1, v1
	s_nop 0
	v_add_f32_e32 v1, 1.0, v1
	v_cmp_gt_f32_e32 vcc, s97, v1
	s_nop 1
	v_cndmask_b32_e64 v76, 0, 32, vcc
	v_ldexp_f32 v1, v1, v76
	v_log_f32_e32 v1, v1
	s_nop 0
	v_mul_f32_e32 v76, 0x3f317217, v1
	v_fma_f32 v76, v1, s28, -v76
	v_fmac_f32_e32 v76, 0x3377d1cf, v1
	v_fmac_f32_e32 v76, 0x3f317217, v1
	v_cmp_lt_f32_e64 s[0:1], |v1|, s29
	s_nop 1
	v_cndmask_b32_e64 v1, v1, v76, s[0:1]
	v_cndmask_b32_e32 v76, 0, v244, vcc
	v_sub_f32_e32 v76, v1, v76
	v_mul_f32_e64 v1, |v81|, s94
	v_exp_f32_e32 v1, v1
	s_nop 0
	v_add_f32_e32 v1, 1.0, v1
	v_cmp_gt_f32_e32 vcc, s97, v1
	s_nop 1
	v_cndmask_b32_e64 v81, 0, 32, vcc
	v_ldexp_f32 v1, v1, v81
	v_log_f32_e32 v1, v1
	s_nop 0
	v_mul_f32_e32 v81, 0x3f317217, v1
	v_fma_f32 v81, v1, s28, -v81
	v_fmac_f32_e32 v81, 0x3377d1cf, v1
	v_fmac_f32_e32 v81, 0x3f317217, v1
	v_cmp_lt_f32_e64 s[0:1], |v1|, s29
	s_nop 1
	v_cndmask_b32_e64 v1, v1, v81, s[0:1]
	v_cndmask_b32_e32 v81, 0, v244, vcc
	v_sub_f32_e32 v81, v1, v81
	v_mul_f32_e64 v1, |v77|, s94
	v_exp_f32_e32 v1, v1
	v_pk_add_f32 v[80:81], v[92:93], v[80:81] neg_lo:[0,1] neg_hi:[0,1]
	v_add_f32_e32 v1, 1.0, v1
	v_cmp_gt_f32_e32 vcc, s97, v1
	v_pk_mul_f32 v[92:93], v[80:81], s[36:37] op_sel_hi:[1,0]
	s_nop 0
	v_cndmask_b32_e64 v77, 0, 32, vcc
	v_ldexp_f32 v1, v1, v77
	v_log_f32_e32 v1, v1
	s_nop 0
	v_mul_f32_e32 v77, 0x3f317217, v1
	v_fma_f32 v77, v1, s28, -v77
	v_fmac_f32_e32 v77, 0x3377d1cf, v1
	v_fmac_f32_e32 v77, 0x3f317217, v1
	v_cmp_lt_f32_e64 s[0:1], |v1|, s29
	s_nop 1
	v_cndmask_b32_e64 v1, v1, v77, s[0:1]
	v_cndmask_b32_e32 v77, 0, v244, vcc
	v_sub_f32_e32 v77, v1, v77
	v_pk_add_f32 v[76:77], v[96:97], v[76:77] neg_lo:[0,1] neg_hi:[0,1]
	s_nop 0
	v_pk_mul_f32 v[96:97], v[76:77], s[36:37] op_sel_hi:[1,0]

.LBB0_1201:
	s_andn2_b64 vcc, exec, s[0:1]
	s_cbranch_vccnz .LBB0_1203
	v_pk_add_f32 v[70:71], v[70:71], v[82:83]
	v_pk_add_f32 v[66:67], v[66:67], v[86:87]
	v_mul_f32_e64 v1, |v70|, s94
	v_exp_f32_e32 v1, v1
	v_mul_f32_e64 v76, |v71|, s94
	v_exp_f32_e32 v76, v76
	v_pk_add_f32 v[72:73], v[72:73], v[84:85]
	v_add_f32_e32 v1, 1.0, v1
	v_cmp_gt_f32_e32 vcc, s97, v1
	v_mul_f32_e64 v77, |v72|, s94
	v_exp_f32_e32 v77, v77
	v_cndmask_b32_e64 v74, 0, 32, vcc
	v_ldexp_f32 v1, v1, v74
	v_log_f32_e32 v1, v1
	v_mul_f32_e64 v74, |v66|, s94
	v_exp_f32_e32 v74, v74
	v_pk_add_f32 v[68:69], v[68:69], v[88:89]
	v_mul_f32_e32 v75, 0x3f317217, v1
	v_fma_f32 v75, v1, s28, -v75
	v_fmac_f32_e32 v75, 0x3377d1cf, v1
	v_fmac_f32_e32 v75, 0x3f317217, v1
	v_cmp_lt_f32_e64 s[0:1], |v1|, s29
	v_add_f32_e32 v74, 1.0, v74
	v_mul_f32_e64 v80, |v73|, s94
	v_cndmask_b32_e64 v1, v1, v75, s[0:1]
	v_cmp_gt_f32_e64 s[0:1], s97, v74
	v_exp_f32_e32 v80, v80
	v_mul_f32_e64 v81, |v69|, s94
	v_cndmask_b32_e64 v75, 0, 32, s[0:1]
	v_ldexp_f32 v74, v74, v75
	v_log_f32_e32 v75, v74
	v_cndmask_b32_e32 v74, 0, v244, vcc
	v_sub_f32_e32 v74, v1, v74
	v_exp_f32_e32 v81, v81
	v_mul_f32_e32 v1, 0x3f317217, v75
	v_fma_f32 v1, v75, s28, -v1
	v_fmac_f32_e32 v1, 0x3377d1cf, v75
	v_fmac_f32_e32 v1, 0x3f317217, v75
	v_cmp_lt_f32_e64 vcc, |v75|, s29
	v_min_f32_e32 v70, 0, v70
	v_min_f32_e32 v71, 0, v71
	v_cndmask_b32_e32 v1, v75, v1, vcc
	v_add_f32_e32 v75, 1.0, v76
	v_cmp_gt_f32_e32 vcc, s97, v75
	v_min_f32_e32 v66, 0, v66
	v_min_f32_e32 v72, 0, v72
	v_cndmask_b32_e64 v76, 0, 32, vcc
	v_ldexp_f32 v75, v75, v76
	v_log_f32_e32 v75, v75
	v_cndmask_b32_e64 v76, 0, v244, s[0:1]
	v_sub_f32_e32 v78, v1, v76
	v_mul_f32_e64 v76, |v67|, s94
	v_mul_f32_e32 v1, 0x3f317217, v75
	v_exp_f32_e32 v76, v76
	v_fma_f32 v1, v75, s28, -v1
	v_fmac_f32_e32 v1, 0x3377d1cf, v75
	v_fmac_f32_e32 v1, 0x3f317217, v75
	v_cmp_lt_f32_e64 s[0:1], |v75|, s29
	v_min_f32_e32 v67, 0, v67
	v_min_f32_e32 v73, 0, v73
	v_cndmask_b32_e64 v1, v75, v1, s[0:1]
	v_add_f32_e32 v75, 1.0, v76
	v_cmp_gt_f32_e64 s[0:1], s97, v75
	v_min_f32_e32 v69, 0, v69
	s_nop 0
	v_cndmask_b32_e64 v76, 0, 32, s[0:1]
	v_ldexp_f32 v75, v75, v76
	v_log_f32_e32 v76, v75
	v_cndmask_b32_e32 v75, 0, v244, vcc
	v_sub_f32_e32 v75, v1, v75
	v_pk_add_f32 v[70:71], v[70:71], v[74:75] neg_lo:[0,1] neg_hi:[0,1]
	v_mul_f32_e32 v1, 0x3f317217, v76
	v_fma_f32 v1, v76, s28, -v1
	v_fmac_f32_e32 v1, 0x3377d1cf, v76
	v_fmac_f32_e32 v1, 0x3f317217, v76
	v_cmp_lt_f32_e64 vcc, |v76|, s29
	s_nop 1
	v_cndmask_b32_e32 v1, v76, v1, vcc
	v_add_f32_e32 v76, 1.0, v77
	v_cmp_gt_f32_e32 vcc, s97, v76
	s_nop 1
	v_cndmask_b32_e64 v77, 0, 32, vcc
	v_ldexp_f32 v76, v76, v77
	v_log_f32_e32 v76, v76
	v_cndmask_b32_e64 v77, 0, v244, s[0:1]
	v_sub_f32_e32 v79, v1, v77
	v_mul_f32_e64 v77, |v68|, s94
	v_mul_f32_e32 v1, 0x3f317217, v76
	v_exp_f32_e32 v77, v77
	v_fma_f32 v1, v76, s28, -v1
	v_fmac_f32_e32 v1, 0x3377d1cf, v76
	v_fmac_f32_e32 v1, 0x3f317217, v76
	v_cmp_lt_f32_e64 s[0:1], |v76|, s29
	v_min_f32_e32 v68, 0, v68
	v_pk_add_f32 v[66:67], v[66:67], v[78:79] neg_lo:[0,1] neg_hi:[0,1]
	v_cndmask_b32_e64 v1, v76, v1, s[0:1]
	v_add_f32_e32 v76, 1.0, v77
	v_cmp_gt_f32_e64 s[0:1], s97, v76
	v_pk_mul_f32 v[78:79], v[66:67], s[36:37] op_sel_hi:[1,0]
	s_nop 0
	v_cndmask_b32_e64 v77, 0, 32, s[0:1]
	v_ldexp_f32 v76, v76, v77
	v_log_f32_e32 v77, v76
	v_cndmask_b32_e32 v76, 0, v244, vcc
	v_sub_f32_e32 v76, v1, v76
	v_mul_f32_e32 v1, 0x3f317217, v77
	v_fma_f32 v1, v77, s28, -v1
	v_fmac_f32_e32 v1, 0x3377d1cf, v77
	v_fmac_f32_e32 v1, 0x3f317217, v77
	v_cmp_lt_f32_e64 vcc, |v77|, s29
	s_nop 1
	v_cndmask_b32_e32 v1, v77, v1, vcc
	v_add_f32_e32 v77, 1.0, v80
	v_cmp_gt_f32_e32 vcc, s97, v77
	s_nop 1
	v_cndmask_b32_e64 v80, 0, 32, vcc
	v_ldexp_f32 v77, v77, v80
	v_log_f32_e32 v77, v77
	v_cndmask_b32_e64 v80, 0, v244, s[0:1]
	v_sub_f32_e32 v80, v1, v80
	v_mul_f32_e32 v1, 0x3f317217, v77
	v_fma_f32 v1, v77, s28, -v1
	v_fmac_f32_e32 v1, 0x3377d1cf, v77
	v_fmac_f32_e32 v1, 0x3f317217, v77
	v_cmp_lt_f32_e64 s[0:1], |v77|, s29
	s_nop 1
	v_cndmask_b32_e64 v1, v77, v1, s[0:1]
	v_cndmask_b32_e32 v77, 0, v244, vcc
	v_sub_f32_e32 v77, v1, v77
	v_add_f32_e32 v1, 1.0, v81
	v_cmp_gt_f32_e32 vcc, s97, v1
	v_pk_add_f32 v[72:73], v[72:73], v[76:77] neg_lo:[0,1] neg_hi:[0,1]
	s_nop 0
	v_cndmask_b32_e64 v74, 0, 32, vcc
	v_ldexp_f32 v1, v1, v74
	v_log_f32_e32 v1, v1
	v_pk_mul_f32 v[74:75], v[70:71], s[36:37] op_sel_hi:[1,0]
	v_pk_mul_f32 v[76:77], v[72:73], s[36:37] op_sel_hi:[1,0]
	v_mul_f32_e32 v70, 0x3f317217, v1
	v_fma_f32 v70, v1, s28, -v70
	v_fmac_f32_e32 v70, 0x3377d1cf, v1
	v_fmac_f32_e32 v70, 0x3f317217, v1
	v_cmp_lt_f32_e64 s[0:1], |v1|, s29
	s_nop 1
	v_cndmask_b32_e64 v1, v1, v70, s[0:1]
	v_cndmask_b32_e32 v70, 0, v244, vcc
	v_sub_f32_e32 v81, v1, v70
	v_pk_add_f32 v[68:69], v[68:69], v[80:81] neg_lo:[0,1] neg_hi:[0,1]
	s_nop 0
	v_pk_mul_f32 v[80:81], v[68:69], s[36:37] op_sel_hi:[1,0]
.LBB0_1203:
	v_lshlrev_b64 v[70:71], 13, v[162:163]
	v_lshl_add_u64 v[70:71], s[34:35], 0, v[70:71]
	v_lshl_add_u64 v[82:83], v[160:161], 1, v[70:71]
	v_add_co_u32_e32 v70, vcc, 0x160000, v82
	v_cvt_pk_bf16_f32 v66, v74, v75
	v_cvt_pk_bf16_f32 v67, v76, v77
	v_cvt_pk_bf16_f32 v68, v78, v79
	v_cvt_pk_bf16_f32 v69, v80, v81
	v_addc_co_u32_e32 v71, vcc, 0, v83, vcc
	global_store_dwordx4 v[70:71], v[66:69], off
	v_mov_b32_e32 v70, 0
	s_and_b64 vcc, exec, s[8:9]
	v_mov_b32_e32 v71, v70
	v_mov_b32_e32 v72, v70
	v_mov_b32_e32 v73, v70
	v_mov_b32_e32 v66, v70
	v_mov_b32_e32 v67, v70
	v_mov_b32_e32 v68, v70
	v_mov_b32_e32 v69, v70
	s_cbranch_vccnz .LBB0_1205
	global_load_dwordx4 v[70:73], v[158:159], off offset:512
	global_load_dwordx4 v[66:69], v[158:159], off offset:528

.LBB0_1218:
	s_andn2_b64 vcc, exec, s[0:1]
	s_cbranch_vccnz .LBB0_1220
	v_pk_add_f32 v[58:59], v[54:55], v[70:71]
	v_pk_add_f32 v[60:61], v[50:51], v[66:67]
	v_mul_f32_e64 v1, |v58|, s94
	v_exp_f32_e32 v1, v1
	v_min_f32_e32 v54, 0, v58
	v_min_f32_e32 v55, 0, v59
	v_pk_add_f32 v[56:57], v[56:57], v[72:73]
	v_add_f32_e32 v1, 1.0, v1
	v_cmp_gt_f32_e32 vcc, s97, v1
	v_pk_add_f32 v[52:53], v[52:53], v[68:69]
	s_nop 0
	v_cndmask_b32_e64 v50, 0, 32, vcc
	v_ldexp_f32 v1, v1, v50
	v_log_f32_e32 v1, v1
	v_min_f32_e32 v64, 0, v52
	v_min_f32_e32 v65, 0, v53
	v_mul_f32_e32 v50, 0x3f317217, v1
	v_fma_f32 v50, v1, s28, -v50
	v_fmac_f32_e32 v50, 0x3377d1cf, v1
	v_fmac_f32_e32 v50, 0x3f317217, v1
	v_cmp_lt_f32_e64 s[0:1], |v1|, s29
	s_nop 1
	v_cndmask_b32_e64 v1, v1, v50, s[0:1]
	v_cndmask_b32_e32 v50, 0, v244, vcc
	v_sub_f32_e32 v58, v1, v50
	v_mul_f32_e64 v1, |v60|, s94
	v_exp_f32_e32 v1, v1
	v_min_f32_e32 v50, 0, v60
	v_add_f32_e32 v1, 1.0, v1
	v_cmp_gt_f32_e32 vcc, s97, v1
	s_nop 1
	v_cndmask_b32_e64 v51, 0, 32, vcc
	v_ldexp_f32 v1, v1, v51
	v_log_f32_e32 v1, v1
	s_nop 0
	v_mul_f32_e32 v51, 0x3f317217, v1
	v_fma_f32 v51, v1, s28, -v51
	v_fmac_f32_e32 v51, 0x3377d1cf, v1
	v_fmac_f32_e32 v51, 0x3f317217, v1
	v_cmp_lt_f32_e64 s[0:1], |v1|, s29
	s_nop 1
	v_cndmask_b32_e64 v1, v1, v51, s[0:1]
	v_cndmask_b32_e32 v51, 0, v244, vcc
	v_sub_f32_e32 v62, v1, v51
	v_mul_f32_e64 v1, |v59|, s94
	v_exp_f32_e32 v1, v1
	s_nop 0
	v_add_f32_e32 v1, 1.0, v1
	v_cmp_gt_f32_e32 vcc, s97, v1
	s_nop 1
	v_cndmask_b32_e64 v51, 0, 32, vcc
	v_ldexp_f32 v1, v1, v51
	v_log_f32_e32 v1, v1
	s_nop 0
	v_mul_f32_e32 v51, 0x3f317217, v1
	v_fma_f32 v51, v1, s28, -v51
	v_fmac_f32_e32 v51, 0x3377d1cf, v1
	v_fmac_f32_e32 v51, 0x3f317217, v1
	v_cmp_lt_f32_e64 s[0:1], |v1|, s29
	s_nop 1
	v_cndmask_b32_e64 v1, v1, v51, s[0:1]
	v_cndmask_b32_e32 v51, 0, v244, vcc
	v_sub_f32_e32 v59, v1, v51
	v_mul_f32_e64 v1, |v61|, s94
	v_exp_f32_e32 v1, v1
	v_min_f32_e32 v51, 0, v61
	v_min_f32_e32 v61, 0, v57
	v_pk_add_f32 v[54:55], v[54:55], v[58:59] neg_lo:[0,1] neg_hi:[0,1]
	v_add_f32_e32 v1, 1.0, v1
	v_cmp_gt_f32_e32 vcc, s97, v1
	v_pk_mul_f32 v[58:59], v[54:55], s[36:37] op_sel_hi:[1,0]
	s_nop 0
	v_cndmask_b32_e64 v60, 0, 32, vcc
	v_ldexp_f32 v1, v1, v60
	v_log_f32_e32 v1, v1
	s_nop 0
	v_mul_f32_e32 v60, 0x3f317217, v1
	v_fma_f32 v60, v1, s28, -v60
	v_fmac_f32_e32 v60, 0x3377d1cf, v1
	v_fmac_f32_e32 v60, 0x3f317217, v1
	v_cmp_lt_f32_e64 s[0:1], |v1|, s29
	s_nop 1
	v_cndmask_b32_e64 v1, v1, v60, s[0:1]
	v_cndmask_b32_e32 v60, 0, v244, vcc
	v_sub_f32_e32 v63, v1, v60
	v_mul_f32_e64 v1, |v56|, s94
	v_exp_f32_e32 v1, v1
	v_min_f32_e32 v60, 0, v56
	v_pk_add_f32 v[50:51], v[50:51], v[62:63] neg_lo:[0,1] neg_hi:[0,1]
	v_add_f32_e32 v1, 1.0, v1
	v_cmp_gt_f32_e32 vcc, s97, v1
	v_pk_mul_f32 v[62:63], v[50:51], s[36:37] op_sel_hi:[1,0]
	s_nop 0
	v_cndmask_b32_e64 v56, 0, 32, vcc
	v_ldexp_f32 v1, v1, v56
	v_log_f32_e32 v1, v1
	s_nop 0
	v_mul_f32_e32 v56, 0x3f317217, v1
	v_fma_f32 v56, v1, s28, -v56
	v_fmac_f32_e32 v56, 0x3377d1cf, v1
	v_fmac_f32_e32 v56, 0x3f317217, v1
	v_cmp_lt_f32_e64 s[0:1], |v1|, s29
	s_nop 1
	v_cndmask_b32_e64 v1, v1, v56, s[0:1]
	v_cndmask_b32_e32 v56, 0, v244, vcc
	v_sub_f32_e32 v56, v1, v56
	v_mul_f32_e64 v1, |v52|, s94
	v_exp_f32_e32 v1, v1
	s_nop 0
	v_add_f32_e32 v1, 1.0, v1
	v_cmp_gt_f32_e32 vcc, s97, v1
	s_nop 1
	v_cndmask_b32_e64 v52, 0, 32, vcc
	v_ldexp_f32 v1, v1, v52
	v_log_f32_e32 v1, v1
	s_nop 0
	v_mul_f32_e32 v52, 0x3f317217, v1
	v_fma_f32 v52, v1, s28, -v52
	v_fmac_f32_e32 v52, 0x3377d1cf, v1
	v_fmac_f32_e32 v52, 0x3f317217, v1
	v_cmp_lt_f32_e64 s[0:1], |v1|, s29
	s_nop 1
	v_cndmask_b32_e64 v1, v1, v52, s[0:1]
	v_cndmask_b32_e32 v52, 0, v244, vcc
	v_sub_f32_e32 v52, v1, v52
	v_mul_f32_e64 v1, |v57|, s94
	v_exp_f32_e32 v1, v1
	s_nop 0
	v_add_f32_e32 v1, 1.0, v1
	v_cmp_gt_f32_e32 vcc, s97, v1
	s_nop 1
	v_cndmask_b32_e64 v57, 0, 32, vcc
	v_ldexp_f32 v1, v1, v57
	v_log_f32_e32 v1, v1
	s_nop 0
	v_mul_f32_e32 v57, 0x3f317217, v1
	v_fma_f32 v57, v1, s28, -v57
	v_fmac_f32_e32 v57, 0x3377d1cf, v1
	v_fmac_f32_e32 v57, 0x3f317217, v1
	v_cmp_lt_f32_e64 s[0:1], |v1|, s29
	s_nop 1
	v_cndmask_b32_e64 v1, v1, v57, s[0:1]
	v_cndmask_b32_e32 v57, 0, v244, vcc
	v_sub_f32_e32 v57, v1, v57
	v_mul_f32_e64 v1, |v53|, s94
	v_exp_f32_e32 v1, v1
	v_pk_add_f32 v[56:57], v[60:61], v[56:57] neg_lo:[0,1] neg_hi:[0,1]
	v_add_f32_e32 v1, 1.0, v1
	v_cmp_gt_f32_e32 vcc, s97, v1
	v_pk_mul_f32 v[60:61], v[56:57], s[36:37] op_sel_hi:[1,0]
	s_nop 0
	v_cndmask_b32_e64 v53, 0, 32, vcc
	v_ldexp_f32 v1, v1, v53
	v_log_f32_e32 v1, v1
	s_nop 0
	v_mul_f32_e32 v53, 0x3f317217, v1
	v_fma_f32 v53, v1, s28, -v53
	v_fmac_f32_e32 v53, 0x3377d1cf, v1
	v_fmac_f32_e32 v53, 0x3f317217, v1
	v_cmp_lt_f32_e64 s[0:1], |v1|, s29
	s_nop 1
	v_cndmask_b32_e64 v1, v1, v53, s[0:1]
	v_cndmask_b32_e32 v53, 0, v244, vcc
	v_sub_f32_e32 v53, v1, v53
	v_pk_add_f32 v[52:53], v[64:65], v[52:53] neg_lo:[0,1] neg_hi:[0,1]
	s_nop 0
	v_pk_mul_f32 v[64:65], v[52:53], s[36:37] op_sel_hi:[1,0]

.LBB0_1224:
	s_andn2_b64 vcc, exec, s[0:1]
	s_cbranch_vccnz .LBB0_1226
	v_pk_add_f32 v[50:51], v[46:47], v[70:71]
	v_pk_add_f32 v[52:53], v[42:43], v[66:67]
	v_mul_f32_e64 v1, |v50|, s94
	v_exp_f32_e32 v1, v1
	v_min_f32_e32 v46, 0, v50
	v_min_f32_e32 v47, 0, v51
	v_pk_add_f32 v[48:49], v[48:49], v[72:73]
	v_add_f32_e32 v1, 1.0, v1
	v_cmp_gt_f32_e32 vcc, s97, v1
	v_pk_add_f32 v[44:45], v[44:45], v[68:69]
	s_nop 0
	v_cndmask_b32_e64 v42, 0, 32, vcc
	v_ldexp_f32 v1, v1, v42
	v_log_f32_e32 v1, v1
	v_min_f32_e32 v56, 0, v44
	v_min_f32_e32 v57, 0, v45
	v_mul_f32_e32 v42, 0x3f317217, v1
	v_fma_f32 v42, v1, s28, -v42
	v_fmac_f32_e32 v42, 0x3377d1cf, v1
	v_fmac_f32_e32 v42, 0x3f317217, v1
	v_cmp_lt_f32_e64 s[0:1], |v1|, s29
	s_nop 1
	v_cndmask_b32_e64 v1, v1, v42, s[0:1]
	v_cndmask_b32_e32 v42, 0, v244, vcc
	v_sub_f32_e32 v50, v1, v42
	v_mul_f32_e64 v1, |v52|, s94
	v_exp_f32_e32 v1, v1
	v_min_f32_e32 v42, 0, v52
	v_add_f32_e32 v1, 1.0, v1
	v_cmp_gt_f32_e32 vcc, s97, v1
	s_nop 1
	v_cndmask_b32_e64 v43, 0, 32, vcc
	v_ldexp_f32 v1, v1, v43
	v_log_f32_e32 v1, v1
	s_nop 0
	v_mul_f32_e32 v43, 0x3f317217, v1
	v_fma_f32 v43, v1, s28, -v43
	v_fmac_f32_e32 v43, 0x3377d1cf, v1
	v_fmac_f32_e32 v43, 0x3f317217, v1
	v_cmp_lt_f32_e64 s[0:1], |v1|, s29
	s_nop 1
	v_cndmask_b32_e64 v1, v1, v43, s[0:1]
	v_cndmask_b32_e32 v43, 0, v244, vcc
	v_sub_f32_e32 v54, v1, v43
	v_mul_f32_e64 v1, |v51|, s94
	v_exp_f32_e32 v1, v1
	s_nop 0
	v_add_f32_e32 v1, 1.0, v1
	v_cmp_gt_f32_e32 vcc, s97, v1
	s_nop 1
	v_cndmask_b32_e64 v43, 0, 32, vcc
	v_ldexp_f32 v1, v1, v43
	v_log_f32_e32 v1, v1
	s_nop 0
	v_mul_f32_e32 v43, 0x3f317217, v1
	v_fma_f32 v43, v1, s28, -v43
	v_fmac_f32_e32 v43, 0x3377d1cf, v1
	v_fmac_f32_e32 v43, 0x3f317217, v1
	v_cmp_lt_f32_e64 s[0:1], |v1|, s29
	s_nop 1
	v_cndmask_b32_e64 v1, v1, v43, s[0:1]
	v_cndmask_b32_e32 v43, 0, v244, vcc
	v_sub_f32_e32 v51, v1, v43
	v_mul_f32_e64 v1, |v53|, s94
	v_exp_f32_e32 v1, v1
	v_min_f32_e32 v43, 0, v53
	v_min_f32_e32 v53, 0, v49
	v_pk_add_f32 v[46:47], v[46:47], v[50:51] neg_lo:[0,1] neg_hi:[0,1]
	v_add_f32_e32 v1, 1.0, v1
	v_cmp_gt_f32_e32 vcc, s97, v1
	v_pk_mul_f32 v[50:51], v[46:47], s[36:37] op_sel_hi:[1,0]
	s_nop 0
	v_cndmask_b32_e64 v52, 0, 32, vcc
	v_ldexp_f32 v1, v1, v52
	v_log_f32_e32 v1, v1
	s_nop 0
	v_mul_f32_e32 v52, 0x3f317217, v1
	v_fma_f32 v52, v1, s28, -v52
	v_fmac_f32_e32 v52, 0x3377d1cf, v1
	v_fmac_f32_e32 v52, 0x3f317217, v1
	v_cmp_lt_f32_e64 s[0:1], |v1|, s29
	s_nop 1
	v_cndmask_b32_e64 v1, v1, v52, s[0:1]
	v_cndmask_b32_e32 v52, 0, v244, vcc
	v_sub_f32_e32 v55, v1, v52
	v_mul_f32_e64 v1, |v48|, s94
	v_exp_f32_e32 v1, v1
	v_min_f32_e32 v52, 0, v48
	v_pk_add_f32 v[42:43], v[42:43], v[54:55] neg_lo:[0,1] neg_hi:[0,1]
	v_add_f32_e32 v1, 1.0, v1
	v_cmp_gt_f32_e32 vcc, s97, v1
	v_pk_mul_f32 v[54:55], v[42:43], s[36:37] op_sel_hi:[1,0]
	s_nop 0
	v_cndmask_b32_e64 v48, 0, 32, vcc
	v_ldexp_f32 v1, v1, v48
	v_log_f32_e32 v1, v1
	s_nop 0
	v_mul_f32_e32 v48, 0x3f317217, v1
	v_fma_f32 v48, v1, s28, -v48
	v_fmac_f32_e32 v48, 0x3377d1cf, v1
	v_fmac_f32_e32 v48, 0x3f317217, v1
	v_cmp_lt_f32_e64 s[0:1], |v1|, s29
	s_nop 1
	v_cndmask_b32_e64 v1, v1, v48, s[0:1]
	v_cndmask_b32_e32 v48, 0, v244, vcc
	v_sub_f32_e32 v48, v1, v48
	v_mul_f32_e64 v1, |v44|, s94
	v_exp_f32_e32 v1, v1
	s_nop 0
	v_add_f32_e32 v1, 1.0, v1
	v_cmp_gt_f32_e32 vcc, s97, v1
	s_nop 1
	v_cndmask_b32_e64 v44, 0, 32, vcc
	v_ldexp_f32 v1, v1, v44
	v_log_f32_e32 v1, v1
	s_nop 0
	v_mul_f32_e32 v44, 0x3f317217, v1
	v_fma_f32 v44, v1, s28, -v44
	v_fmac_f32_e32 v44, 0x3377d1cf, v1
	v_fmac_f32_e32 v44, 0x3f317217, v1
	v_cmp_lt_f32_e64 s[0:1], |v1|, s29
	s_nop 1
	v_cndmask_b32_e64 v1, v1, v44, s[0:1]
	v_cndmask_b32_e32 v44, 0, v244, vcc
	v_sub_f32_e32 v44, v1, v44
	v_mul_f32_e64 v1, |v49|, s94
	v_exp_f32_e32 v1, v1
	s_nop 0
	v_add_f32_e32 v1, 1.0, v1
	v_cmp_gt_f32_e32 vcc, s97, v1
	s_nop 1
	v_cndmask_b32_e64 v49, 0, 32, vcc
	v_ldexp_f32 v1, v1, v49
	v_log_f32_e32 v1, v1
	s_nop 0
	v_mul_f32_e32 v49, 0x3f317217, v1
	v_fma_f32 v49, v1, s28, -v49
	v_fmac_f32_e32 v49, 0x3377d1cf, v1
	v_fmac_f32_e32 v49, 0x3f317217, v1
	v_cmp_lt_f32_e64 s[0:1], |v1|, s29
	s_nop 1
	v_cndmask_b32_e64 v1, v1, v49, s[0:1]
	v_cndmask_b32_e32 v49, 0, v244, vcc
	v_sub_f32_e32 v49, v1, v49
	v_mul_f32_e64 v1, |v45|, s94
	v_exp_f32_e32 v1, v1
	v_pk_add_f32 v[48:49], v[52:53], v[48:49] neg_lo:[0,1] neg_hi:[0,1]
	v_add_f32_e32 v1, 1.0, v1
	v_cmp_gt_f32_e32 vcc, s97, v1
	v_pk_mul_f32 v[52:53], v[48:49], s[36:37] op_sel_hi:[1,0]
	s_nop 0
	v_cndmask_b32_e64 v45, 0, 32, vcc
	v_ldexp_f32 v1, v1, v45
	v_log_f32_e32 v1, v1
	s_nop 0
	v_mul_f32_e32 v45, 0x3f317217, v1
	v_fma_f32 v45, v1, s28, -v45
	v_fmac_f32_e32 v45, 0x3377d1cf, v1
	v_fmac_f32_e32 v45, 0x3f317217, v1
	v_cmp_lt_f32_e64 s[0:1], |v1|, s29
	s_nop 1
	v_cndmask_b32_e64 v1, v1, v45, s[0:1]
	v_cndmask_b32_e32 v45, 0, v244, vcc
	v_sub_f32_e32 v45, v1, v45
	v_pk_add_f32 v[44:45], v[56:57], v[44:45] neg_lo:[0,1] neg_hi:[0,1]
	s_nop 0
	v_pk_mul_f32 v[56:57], v[44:45], s[36:37] op_sel_hi:[1,0]

.LBB0_1230:
	s_andn2_b64 vcc, exec, s[0:1]
	s_cbranch_vccnz .LBB0_1232
	v_pk_add_f32 v[42:43], v[38:39], v[70:71]
	v_pk_add_f32 v[44:45], v[34:35], v[66:67]
	v_mul_f32_e64 v1, |v42|, s94
	v_exp_f32_e32 v1, v1
	v_min_f32_e32 v38, 0, v42
	v_min_f32_e32 v39, 0, v43
	v_pk_add_f32 v[40:41], v[40:41], v[72:73]
	v_add_f32_e32 v1, 1.0, v1
	v_cmp_gt_f32_e32 vcc, s97, v1
	v_pk_add_f32 v[36:37], v[36:37], v[68:69]
	s_nop 0
	v_cndmask_b32_e64 v34, 0, 32, vcc
	v_ldexp_f32 v1, v1, v34
	v_log_f32_e32 v1, v1
	v_min_f32_e32 v48, 0, v36
	v_min_f32_e32 v49, 0, v37
	v_mul_f32_e32 v34, 0x3f317217, v1
	v_fma_f32 v34, v1, s28, -v34
	v_fmac_f32_e32 v34, 0x3377d1cf, v1
	v_fmac_f32_e32 v34, 0x3f317217, v1
	v_cmp_lt_f32_e64 s[0:1], |v1|, s29
	s_nop 1
	v_cndmask_b32_e64 v1, v1, v34, s[0:1]
	v_cndmask_b32_e32 v34, 0, v244, vcc
	v_sub_f32_e32 v42, v1, v34
	v_mul_f32_e64 v1, |v44|, s94
	v_exp_f32_e32 v1, v1
	v_min_f32_e32 v34, 0, v44
	v_add_f32_e32 v1, 1.0, v1
	v_cmp_gt_f32_e32 vcc, s97, v1
	s_nop 1
	v_cndmask_b32_e64 v35, 0, 32, vcc
	v_ldexp_f32 v1, v1, v35
	v_log_f32_e32 v1, v1
	s_nop 0
	v_mul_f32_e32 v35, 0x3f317217, v1
	v_fma_f32 v35, v1, s28, -v35
	v_fmac_f32_e32 v35, 0x3377d1cf, v1
	v_fmac_f32_e32 v35, 0x3f317217, v1
	v_cmp_lt_f32_e64 s[0:1], |v1|, s29
	s_nop 1
	v_cndmask_b32_e64 v1, v1, v35, s[0:1]
	v_cndmask_b32_e32 v35, 0, v244, vcc
	v_sub_f32_e32 v46, v1, v35
	v_mul_f32_e64 v1, |v43|, s94
	v_exp_f32_e32 v1, v1
	s_nop 0
	v_add_f32_e32 v1, 1.0, v1
	v_cmp_gt_f32_e32 vcc, s97, v1
	s_nop 1
	v_cndmask_b32_e64 v35, 0, 32, vcc
	v_ldexp_f32 v1, v1, v35
	v_log_f32_e32 v1, v1
	s_nop 0
	v_mul_f32_e32 v35, 0x3f317217, v1
	v_fma_f32 v35, v1, s28, -v35
	v_fmac_f32_e32 v35, 0x3377d1cf, v1
	v_fmac_f32_e32 v35, 0x3f317217, v1
	v_cmp_lt_f32_e64 s[0:1], |v1|, s29
	s_nop 1
	v_cndmask_b32_e64 v1, v1, v35, s[0:1]
	v_cndmask_b32_e32 v35, 0, v244, vcc
	v_sub_f32_e32 v43, v1, v35
	v_mul_f32_e64 v1, |v45|, s94
	v_exp_f32_e32 v1, v1
	v_min_f32_e32 v35, 0, v45
	v_min_f32_e32 v45, 0, v41
	v_pk_add_f32 v[38:39], v[38:39], v[42:43] neg_lo:[0,1] neg_hi:[0,1]
	v_add_f32_e32 v1, 1.0, v1
	v_cmp_gt_f32_e32 vcc, s97, v1
	v_pk_mul_f32 v[42:43], v[38:39], s[36:37] op_sel_hi:[1,0]
	s_nop 0
	v_cndmask_b32_e64 v44, 0, 32, vcc
	v_ldexp_f32 v1, v1, v44
	v_log_f32_e32 v1, v1
	s_nop 0
	v_mul_f32_e32 v44, 0x3f317217, v1
	v_fma_f32 v44, v1, s28, -v44
	v_fmac_f32_e32 v44, 0x3377d1cf, v1
	v_fmac_f32_e32 v44, 0x3f317217, v1
	v_cmp_lt_f32_e64 s[0:1], |v1|, s29
	s_nop 1
	v_cndmask_b32_e64 v1, v1, v44, s[0:1]
	v_cndmask_b32_e32 v44, 0, v244, vcc
	v_sub_f32_e32 v47, v1, v44
	v_mul_f32_e64 v1, |v40|, s94
	v_exp_f32_e32 v1, v1
	v_min_f32_e32 v44, 0, v40
	v_pk_add_f32 v[34:35], v[34:35], v[46:47] neg_lo:[0,1] neg_hi:[0,1]
	v_add_f32_e32 v1, 1.0, v1
	v_cmp_gt_f32_e32 vcc, s97, v1
	v_pk_mul_f32 v[46:47], v[34:35], s[36:37] op_sel_hi:[1,0]
	s_nop 0
	v_cndmask_b32_e64 v40, 0, 32, vcc
	v_ldexp_f32 v1, v1, v40
	v_log_f32_e32 v1, v1
	s_nop 0
	v_mul_f32_e32 v40, 0x3f317217, v1
	v_fma_f32 v40, v1, s28, -v40
	v_fmac_f32_e32 v40, 0x3377d1cf, v1
	v_fmac_f32_e32 v40, 0x3f317217, v1
	v_cmp_lt_f32_e64 s[0:1], |v1|, s29
	s_nop 1
	v_cndmask_b32_e64 v1, v1, v40, s[0:1]
	v_cndmask_b32_e32 v40, 0, v244, vcc
	v_sub_f32_e32 v40, v1, v40
	v_mul_f32_e64 v1, |v36|, s94
	v_exp_f32_e32 v1, v1
	s_nop 0
	v_add_f32_e32 v1, 1.0, v1
	v_cmp_gt_f32_e32 vcc, s97, v1
	s_nop 1
	v_cndmask_b32_e64 v36, 0, 32, vcc
	v_ldexp_f32 v1, v1, v36
	v_log_f32_e32 v1, v1
	s_nop 0
	v_mul_f32_e32 v36, 0x3f317217, v1
	v_fma_f32 v36, v1, s28, -v36
	v_fmac_f32_e32 v36, 0x3377d1cf, v1
	v_fmac_f32_e32 v36, 0x3f317217, v1
	v_cmp_lt_f32_e64 s[0:1], |v1|, s29
	s_nop 1
	v_cndmask_b32_e64 v1, v1, v36, s[0:1]
	v_cndmask_b32_e32 v36, 0, v244, vcc
	v_sub_f32_e32 v36, v1, v36
	v_mul_f32_e64 v1, |v41|, s94
	v_exp_f32_e32 v1, v1
	s_nop 0
	v_add_f32_e32 v1, 1.0, v1
	v_cmp_gt_f32_e32 vcc, s97, v1
	s_nop 1
	v_cndmask_b32_e64 v41, 0, 32, vcc
	v_ldexp_f32 v1, v1, v41
	v_log_f32_e32 v1, v1
	s_nop 0
	v_mul_f32_e32 v41, 0x3f317217, v1
	v_fma_f32 v41, v1, s28, -v41
	v_fmac_f32_e32 v41, 0x3377d1cf, v1
	v_fmac_f32_e32 v41, 0x3f317217, v1
	v_cmp_lt_f32_e64 s[0:1], |v1|, s29
	s_nop 1
	v_cndmask_b32_e64 v1, v1, v41, s[0:1]
	v_cndmask_b32_e32 v41, 0, v244, vcc
	v_sub_f32_e32 v41, v1, v41
	v_mul_f32_e64 v1, |v37|, s94
	v_exp_f32_e32 v1, v1
	v_pk_add_f32 v[40:41], v[44:45], v[40:41] neg_lo:[0,1] neg_hi:[0,1]
	v_add_f32_e32 v1, 1.0, v1
	v_cmp_gt_f32_e32 vcc, s97, v1
	v_pk_mul_f32 v[44:45], v[40:41], s[36:37] op_sel_hi:[1,0]
	s_nop 0
	v_cndmask_b32_e64 v37, 0, 32, vcc
	v_ldexp_f32 v1, v1, v37
	v_log_f32_e32 v1, v1
	s_nop 0
	v_mul_f32_e32 v37, 0x3f317217, v1
	v_fma_f32 v37, v1, s28, -v37
	v_fmac_f32_e32 v37, 0x3377d1cf, v1
	v_fmac_f32_e32 v37, 0x3f317217, v1
	v_cmp_lt_f32_e64 s[0:1], |v1|, s29
	s_nop 1
	v_cndmask_b32_e64 v1, v1, v37, s[0:1]
	v_cndmask_b32_e32 v37, 0, v244, vcc
	v_sub_f32_e32 v37, v1, v37
	v_pk_add_f32 v[36:37], v[48:49], v[36:37] neg_lo:[0,1] neg_hi:[0,1]
	s_nop 0
	v_pk_mul_f32 v[48:49], v[36:37], s[36:37] op_sel_hi:[1,0]

.LBB0_1236:
	s_andn2_b64 vcc, exec, s[0:1]
	s_cbranch_vccnz .LBB0_1238
	v_pk_add_f32 v[34:35], v[30:31], v[70:71]
	v_pk_add_f32 v[36:37], v[26:27], v[66:67]
	v_mul_f32_e64 v1, |v34|, s94
	v_exp_f32_e32 v1, v1
	v_min_f32_e32 v30, 0, v34
	v_min_f32_e32 v31, 0, v35
	v_pk_add_f32 v[32:33], v[32:33], v[72:73]
	v_add_f32_e32 v1, 1.0, v1
	v_cmp_gt_f32_e32 vcc, s97, v1
	v_pk_add_f32 v[28:29], v[28:29], v[68:69]
	s_nop 0
	v_cndmask_b32_e64 v26, 0, 32, vcc
	v_ldexp_f32 v1, v1, v26
	v_log_f32_e32 v1, v1
	v_min_f32_e32 v40, 0, v28
	v_min_f32_e32 v41, 0, v29
	v_mul_f32_e32 v26, 0x3f317217, v1
	v_fma_f32 v26, v1, s28, -v26
	v_fmac_f32_e32 v26, 0x3377d1cf, v1
	v_fmac_f32_e32 v26, 0x3f317217, v1
	v_cmp_lt_f32_e64 s[0:1], |v1|, s29
	s_nop 1
	v_cndmask_b32_e64 v1, v1, v26, s[0:1]
	v_cndmask_b32_e32 v26, 0, v244, vcc
	v_sub_f32_e32 v34, v1, v26
	v_mul_f32_e64 v1, |v36|, s94
	v_exp_f32_e32 v1, v1
	v_min_f32_e32 v26, 0, v36
	v_add_f32_e32 v1, 1.0, v1
	v_cmp_gt_f32_e32 vcc, s97, v1
	s_nop 1
	v_cndmask_b32_e64 v27, 0, 32, vcc
	v_ldexp_f32 v1, v1, v27
	v_log_f32_e32 v1, v1
	s_nop 0
	v_mul_f32_e32 v27, 0x3f317217, v1
	v_fma_f32 v27, v1, s28, -v27
	v_fmac_f32_e32 v27, 0x3377d1cf, v1
	v_fmac_f32_e32 v27, 0x3f317217, v1
	v_cmp_lt_f32_e64 s[0:1], |v1|, s29
	s_nop 1
	v_cndmask_b32_e64 v1, v1, v27, s[0:1]
	v_cndmask_b32_e32 v27, 0, v244, vcc
	v_sub_f32_e32 v38, v1, v27
	v_mul_f32_e64 v1, |v35|, s94
	v_exp_f32_e32 v1, v1
	s_nop 0
	v_add_f32_e32 v1, 1.0, v1
	v_cmp_gt_f32_e32 vcc, s97, v1
	s_nop 1
	v_cndmask_b32_e64 v27, 0, 32, vcc
	v_ldexp_f32 v1, v1, v27
	v_log_f32_e32 v1, v1
	s_nop 0
	v_mul_f32_e32 v27, 0x3f317217, v1
	v_fma_f32 v27, v1, s28, -v27
	v_fmac_f32_e32 v27, 0x3377d1cf, v1
	v_fmac_f32_e32 v27, 0x3f317217, v1
	v_cmp_lt_f32_e64 s[0:1], |v1|, s29
	s_nop 1
	v_cndmask_b32_e64 v1, v1, v27, s[0:1]
	v_cndmask_b32_e32 v27, 0, v244, vcc
	v_sub_f32_e32 v35, v1, v27
	v_mul_f32_e64 v1, |v37|, s94
	v_exp_f32_e32 v1, v1
	v_min_f32_e32 v27, 0, v37
	v_min_f32_e32 v37, 0, v33
	v_pk_add_f32 v[30:31], v[30:31], v[34:35] neg_lo:[0,1] neg_hi:[0,1]
	v_add_f32_e32 v1, 1.0, v1
	v_cmp_gt_f32_e32 vcc, s97, v1
	v_pk_mul_f32 v[34:35], v[30:31], s[36:37] op_sel_hi:[1,0]
	s_nop 0
	v_cndmask_b32_e64 v36, 0, 32, vcc
	v_ldexp_f32 v1, v1, v36
	v_log_f32_e32 v1, v1
	s_nop 0
	v_mul_f32_e32 v36, 0x3f317217, v1
	v_fma_f32 v36, v1, s28, -v36
	v_fmac_f32_e32 v36, 0x3377d1cf, v1
	v_fmac_f32_e32 v36, 0x3f317217, v1
	v_cmp_lt_f32_e64 s[0:1], |v1|, s29
	s_nop 1
	v_cndmask_b32_e64 v1, v1, v36, s[0:1]
	v_cndmask_b32_e32 v36, 0, v244, vcc
	v_sub_f32_e32 v39, v1, v36
	v_mul_f32_e64 v1, |v32|, s94
	v_exp_f32_e32 v1, v1
	v_min_f32_e32 v36, 0, v32
	v_pk_add_f32 v[26:27], v[26:27], v[38:39] neg_lo:[0,1] neg_hi:[0,1]
	v_add_f32_e32 v1, 1.0, v1
	v_cmp_gt_f32_e32 vcc, s97, v1
	v_pk_mul_f32 v[38:39], v[26:27], s[36:37] op_sel_hi:[1,0]
	s_nop 0
	v_cndmask_b32_e64 v32, 0, 32, vcc
	v_ldexp_f32 v1, v1, v32
	v_log_f32_e32 v1, v1
	s_nop 0
	v_mul_f32_e32 v32, 0x3f317217, v1
	v_fma_f32 v32, v1, s28, -v32
	v_fmac_f32_e32 v32, 0x3377d1cf, v1
	v_fmac_f32_e32 v32, 0x3f317217, v1
	v_cmp_lt_f32_e64 s[0:1], |v1|, s29
	s_nop 1
	v_cndmask_b32_e64 v1, v1, v32, s[0:1]
	v_cndmask_b32_e32 v32, 0, v244, vcc
	v_sub_f32_e32 v32, v1, v32
	v_mul_f32_e64 v1, |v28|, s94
	v_exp_f32_e32 v1, v1
	s_nop 0
	v_add_f32_e32 v1, 1.0, v1
	v_cmp_gt_f32_e32 vcc, s97, v1
	s_nop 1
	v_cndmask_b32_e64 v28, 0, 32, vcc
	v_ldexp_f32 v1, v1, v28
	v_log_f32_e32 v1, v1
	s_nop 0
	v_mul_f32_e32 v28, 0x3f317217, v1
	v_fma_f32 v28, v1, s28, -v28
	v_fmac_f32_e32 v28, 0x3377d1cf, v1
	v_fmac_f32_e32 v28, 0x3f317217, v1
	v_cmp_lt_f32_e64 s[0:1], |v1|, s29
	s_nop 1
	v_cndmask_b32_e64 v1, v1, v28, s[0:1]
	v_cndmask_b32_e32 v28, 0, v244, vcc
	v_sub_f32_e32 v28, v1, v28
	v_mul_f32_e64 v1, |v33|, s94
	v_exp_f32_e32 v1, v1
	s_nop 0
	v_add_f32_e32 v1, 1.0, v1
	v_cmp_gt_f32_e32 vcc, s97, v1
	s_nop 1
	v_cndmask_b32_e64 v33, 0, 32, vcc
	v_ldexp_f32 v1, v1, v33
	v_log_f32_e32 v1, v1
	s_nop 0
	v_mul_f32_e32 v33, 0x3f317217, v1
	v_fma_f32 v33, v1, s28, -v33
	v_fmac_f32_e32 v33, 0x3377d1cf, v1
	v_fmac_f32_e32 v33, 0x3f317217, v1
	v_cmp_lt_f32_e64 s[0:1], |v1|, s29
	s_nop 1
	v_cndmask_b32_e64 v1, v1, v33, s[0:1]
	v_cndmask_b32_e32 v33, 0, v244, vcc
	v_sub_f32_e32 v33, v1, v33
	v_mul_f32_e64 v1, |v29|, s94
	v_exp_f32_e32 v1, v1
	v_pk_add_f32 v[32:33], v[36:37], v[32:33] neg_lo:[0,1] neg_hi:[0,1]
	v_add_f32_e32 v1, 1.0, v1
	v_cmp_gt_f32_e32 vcc, s97, v1
	v_pk_mul_f32 v[36:37], v[32:33], s[36:37] op_sel_hi:[1,0]
	s_nop 0
	v_cndmask_b32_e64 v29, 0, 32, vcc
	v_ldexp_f32 v1, v1, v29
	v_log_f32_e32 v1, v1
	s_nop 0
	v_mul_f32_e32 v29, 0x3f317217, v1
	v_fma_f32 v29, v1, s28, -v29
	v_fmac_f32_e32 v29, 0x3377d1cf, v1
	v_fmac_f32_e32 v29, 0x3f317217, v1
	v_cmp_lt_f32_e64 s[0:1], |v1|, s29
	s_nop 1
	v_cndmask_b32_e64 v1, v1, v29, s[0:1]
	v_cndmask_b32_e32 v29, 0, v244, vcc
	v_sub_f32_e32 v29, v1, v29
	v_pk_add_f32 v[28:29], v[40:41], v[28:29] neg_lo:[0,1] neg_hi:[0,1]
	s_nop 0
	v_pk_mul_f32 v[40:41], v[28:29], s[36:37] op_sel_hi:[1,0]

.LBB0_1242:
	s_andn2_b64 vcc, exec, s[0:1]
	s_cbranch_vccnz .LBB0_1244
	v_pk_add_f32 v[26:27], v[22:23], v[70:71]
	v_pk_add_f32 v[28:29], v[18:19], v[66:67]
	v_mul_f32_e64 v1, |v26|, s94
	v_exp_f32_e32 v1, v1
	v_min_f32_e32 v22, 0, v26
	v_min_f32_e32 v23, 0, v27
	v_pk_add_f32 v[24:25], v[24:25], v[72:73]
	v_add_f32_e32 v1, 1.0, v1
	v_cmp_gt_f32_e32 vcc, s97, v1
	v_pk_add_f32 v[20:21], v[20:21], v[68:69]
	s_nop 0
	v_cndmask_b32_e64 v18, 0, 32, vcc
	v_ldexp_f32 v1, v1, v18
	v_log_f32_e32 v1, v1
	v_min_f32_e32 v32, 0, v20
	v_min_f32_e32 v33, 0, v21
	v_mul_f32_e32 v18, 0x3f317217, v1
	v_fma_f32 v18, v1, s28, -v18
	v_fmac_f32_e32 v18, 0x3377d1cf, v1
	v_fmac_f32_e32 v18, 0x3f317217, v1
	v_cmp_lt_f32_e64 s[0:1], |v1|, s29
	s_nop 1
	v_cndmask_b32_e64 v1, v1, v18, s[0:1]
	v_cndmask_b32_e32 v18, 0, v244, vcc
	v_sub_f32_e32 v26, v1, v18
	v_mul_f32_e64 v1, |v28|, s94
	v_exp_f32_e32 v1, v1
	v_min_f32_e32 v18, 0, v28
	v_add_f32_e32 v1, 1.0, v1
	v_cmp_gt_f32_e32 vcc, s97, v1
	s_nop 1
	v_cndmask_b32_e64 v19, 0, 32, vcc
	v_ldexp_f32 v1, v1, v19
	v_log_f32_e32 v1, v1
	s_nop 0
	v_mul_f32_e32 v19, 0x3f317217, v1
	v_fma_f32 v19, v1, s28, -v19
	v_fmac_f32_e32 v19, 0x3377d1cf, v1
	v_fmac_f32_e32 v19, 0x3f317217, v1
	v_cmp_lt_f32_e64 s[0:1], |v1|, s29
	s_nop 1
	v_cndmask_b32_e64 v1, v1, v19, s[0:1]
	v_cndmask_b32_e32 v19, 0, v244, vcc
	v_sub_f32_e32 v30, v1, v19
	v_mul_f32_e64 v1, |v27|, s94
	v_exp_f32_e32 v1, v1
	s_nop 0
	v_add_f32_e32 v1, 1.0, v1
	v_cmp_gt_f32_e32 vcc, s97, v1
	s_nop 1
	v_cndmask_b32_e64 v19, 0, 32, vcc
	v_ldexp_f32 v1, v1, v19
	v_log_f32_e32 v1, v1
	s_nop 0
	v_mul_f32_e32 v19, 0x3f317217, v1
	v_fma_f32 v19, v1, s28, -v19
	v_fmac_f32_e32 v19, 0x3377d1cf, v1
	v_fmac_f32_e32 v19, 0x3f317217, v1
	v_cmp_lt_f32_e64 s[0:1], |v1|, s29
	s_nop 1
	v_cndmask_b32_e64 v1, v1, v19, s[0:1]
	v_cndmask_b32_e32 v19, 0, v244, vcc
	v_sub_f32_e32 v27, v1, v19
	v_mul_f32_e64 v1, |v29|, s94
	v_exp_f32_e32 v1, v1
	v_min_f32_e32 v19, 0, v29
	v_min_f32_e32 v29, 0, v25
	v_pk_add_f32 v[22:23], v[22:23], v[26:27] neg_lo:[0,1] neg_hi:[0,1]
	v_add_f32_e32 v1, 1.0, v1
	v_cmp_gt_f32_e32 vcc, s97, v1
	v_pk_mul_f32 v[26:27], v[22:23], s[36:37] op_sel_hi:[1,0]
	s_nop 0
	v_cndmask_b32_e64 v28, 0, 32, vcc
	v_ldexp_f32 v1, v1, v28
	v_log_f32_e32 v1, v1
	s_nop 0
	v_mul_f32_e32 v28, 0x3f317217, v1
	v_fma_f32 v28, v1, s28, -v28
	v_fmac_f32_e32 v28, 0x3377d1cf, v1
	v_fmac_f32_e32 v28, 0x3f317217, v1
	v_cmp_lt_f32_e64 s[0:1], |v1|, s29
	s_nop 1
	v_cndmask_b32_e64 v1, v1, v28, s[0:1]
	v_cndmask_b32_e32 v28, 0, v244, vcc
	v_sub_f32_e32 v31, v1, v28
	v_mul_f32_e64 v1, |v24|, s94
	v_exp_f32_e32 v1, v1
	v_min_f32_e32 v28, 0, v24
	v_pk_add_f32 v[18:19], v[18:19], v[30:31] neg_lo:[0,1] neg_hi:[0,1]
	v_add_f32_e32 v1, 1.0, v1
	v_cmp_gt_f32_e32 vcc, s97, v1
	v_pk_mul_f32 v[30:31], v[18:19], s[36:37] op_sel_hi:[1,0]
	s_nop 0
	v_cndmask_b32_e64 v24, 0, 32, vcc
	v_ldexp_f32 v1, v1, v24
	v_log_f32_e32 v1, v1
	s_nop 0
	v_mul_f32_e32 v24, 0x3f317217, v1
	v_fma_f32 v24, v1, s28, -v24
	v_fmac_f32_e32 v24, 0x3377d1cf, v1
	v_fmac_f32_e32 v24, 0x3f317217, v1
	v_cmp_lt_f32_e64 s[0:1], |v1|, s29
	s_nop 1
	v_cndmask_b32_e64 v1, v1, v24, s[0:1]
	v_cndmask_b32_e32 v24, 0, v244, vcc
	v_sub_f32_e32 v24, v1, v24
	v_mul_f32_e64 v1, |v20|, s94
	v_exp_f32_e32 v1, v1
	s_nop 0
	v_add_f32_e32 v1, 1.0, v1
	v_cmp_gt_f32_e32 vcc, s97, v1
	s_nop 1
	v_cndmask_b32_e64 v20, 0, 32, vcc
	v_ldexp_f32 v1, v1, v20
	v_log_f32_e32 v1, v1
	s_nop 0
	v_mul_f32_e32 v20, 0x3f317217, v1
	v_fma_f32 v20, v1, s28, -v20
	v_fmac_f32_e32 v20, 0x3377d1cf, v1
	v_fmac_f32_e32 v20, 0x3f317217, v1
	v_cmp_lt_f32_e64 s[0:1], |v1|, s29
	s_nop 1
	v_cndmask_b32_e64 v1, v1, v20, s[0:1]
	v_cndmask_b32_e32 v20, 0, v244, vcc
	v_sub_f32_e32 v20, v1, v20
	v_mul_f32_e64 v1, |v25|, s94
	v_exp_f32_e32 v1, v1
	s_nop 0
	v_add_f32_e32 v1, 1.0, v1
	v_cmp_gt_f32_e32 vcc, s97, v1
	s_nop 1
	v_cndmask_b32_e64 v25, 0, 32, vcc
	v_ldexp_f32 v1, v1, v25
	v_log_f32_e32 v1, v1
	s_nop 0
	v_mul_f32_e32 v25, 0x3f317217, v1
	v_fma_f32 v25, v1, s28, -v25
	v_fmac_f32_e32 v25, 0x3377d1cf, v1
	v_fmac_f32_e32 v25, 0x3f317217, v1
	v_cmp_lt_f32_e64 s[0:1], |v1|, s29
	s_nop 1
	v_cndmask_b32_e64 v1, v1, v25, s[0:1]
	v_cndmask_b32_e32 v25, 0, v244, vcc
	v_sub_f32_e32 v25, v1, v25
	v_mul_f32_e64 v1, |v21|, s94
	v_exp_f32_e32 v1, v1
	v_pk_add_f32 v[24:25], v[28:29], v[24:25] neg_lo:[0,1] neg_hi:[0,1]
	v_add_f32_e32 v1, 1.0, v1
	v_cmp_gt_f32_e32 vcc, s97, v1
	v_pk_mul_f32 v[28:29], v[24:25], s[36:37] op_sel_hi:[1,0]
	s_nop 0
	v_cndmask_b32_e64 v21, 0, 32, vcc
	v_ldexp_f32 v1, v1, v21
	v_log_f32_e32 v1, v1
	s_nop 0
	v_mul_f32_e32 v21, 0x3f317217, v1
	v_fma_f32 v21, v1, s28, -v21
	v_fmac_f32_e32 v21, 0x3377d1cf, v1
	v_fmac_f32_e32 v21, 0x3f317217, v1
	v_cmp_lt_f32_e64 s[0:1], |v1|, s29
	s_nop 1
	v_cndmask_b32_e64 v1, v1, v21, s[0:1]
	v_cndmask_b32_e32 v21, 0, v244, vcc
	v_sub_f32_e32 v21, v1, v21
	v_pk_add_f32 v[20:21], v[32:33], v[20:21] neg_lo:[0,1] neg_hi:[0,1]
	s_nop 0
	v_pk_mul_f32 v[32:33], v[20:21], s[36:37] op_sel_hi:[1,0]

.LBB0_1248:
	s_andn2_b64 vcc, exec, s[0:1]
	s_cbranch_vccnz .LBB0_1250
	v_pk_add_f32 v[18:19], v[14:15], v[70:71]
	v_pk_add_f32 v[20:21], v[10:11], v[66:67]
	v_mul_f32_e64 v1, |v18|, s94
	v_exp_f32_e32 v1, v1
	v_min_f32_e32 v14, 0, v18
	v_min_f32_e32 v15, 0, v19
	v_pk_add_f32 v[16:17], v[16:17], v[72:73]
	v_add_f32_e32 v1, 1.0, v1
	v_cmp_gt_f32_e32 vcc, s97, v1
	v_pk_add_f32 v[12:13], v[12:13], v[68:69]
	s_nop 0
	v_cndmask_b32_e64 v10, 0, 32, vcc
	v_ldexp_f32 v1, v1, v10
	v_log_f32_e32 v1, v1
	v_min_f32_e32 v24, 0, v12
	v_min_f32_e32 v25, 0, v13
	v_mul_f32_e32 v10, 0x3f317217, v1
	v_fma_f32 v10, v1, s28, -v10
	v_fmac_f32_e32 v10, 0x3377d1cf, v1
	v_fmac_f32_e32 v10, 0x3f317217, v1
	v_cmp_lt_f32_e64 s[0:1], |v1|, s29
	s_nop 1
	v_cndmask_b32_e64 v1, v1, v10, s[0:1]
	v_cndmask_b32_e32 v10, 0, v244, vcc
	v_sub_f32_e32 v18, v1, v10
	v_mul_f32_e64 v1, |v20|, s94
	v_exp_f32_e32 v1, v1
	v_min_f32_e32 v10, 0, v20
	v_add_f32_e32 v1, 1.0, v1
	v_cmp_gt_f32_e32 vcc, s97, v1
	s_nop 1
	v_cndmask_b32_e64 v11, 0, 32, vcc
	v_ldexp_f32 v1, v1, v11
	v_log_f32_e32 v1, v1
	s_nop 0
	v_mul_f32_e32 v11, 0x3f317217, v1
	v_fma_f32 v11, v1, s28, -v11
	v_fmac_f32_e32 v11, 0x3377d1cf, v1
	v_fmac_f32_e32 v11, 0x3f317217, v1
	v_cmp_lt_f32_e64 s[0:1], |v1|, s29
	s_nop 1
	v_cndmask_b32_e64 v1, v1, v11, s[0:1]
	v_cndmask_b32_e32 v11, 0, v244, vcc
	v_sub_f32_e32 v22, v1, v11
	v_mul_f32_e64 v1, |v19|, s94
	v_exp_f32_e32 v1, v1
	s_nop 0
	v_add_f32_e32 v1, 1.0, v1
	v_cmp_gt_f32_e32 vcc, s97, v1
	s_nop 1
	v_cndmask_b32_e64 v11, 0, 32, vcc
	v_ldexp_f32 v1, v1, v11
	v_log_f32_e32 v1, v1
	s_nop 0
	v_mul_f32_e32 v11, 0x3f317217, v1
	v_fma_f32 v11, v1, s28, -v11
	v_fmac_f32_e32 v11, 0x3377d1cf, v1
	v_fmac_f32_e32 v11, 0x3f317217, v1
	v_cmp_lt_f32_e64 s[0:1], |v1|, s29
	s_nop 1
	v_cndmask_b32_e64 v1, v1, v11, s[0:1]
	v_cndmask_b32_e32 v11, 0, v244, vcc
	v_sub_f32_e32 v19, v1, v11
	v_mul_f32_e64 v1, |v21|, s94
	v_exp_f32_e32 v1, v1
	v_min_f32_e32 v11, 0, v21
	v_min_f32_e32 v21, 0, v17
	v_pk_add_f32 v[14:15], v[14:15], v[18:19] neg_lo:[0,1] neg_hi:[0,1]
	v_add_f32_e32 v1, 1.0, v1
	v_cmp_gt_f32_e32 vcc, s97, v1
	v_pk_mul_f32 v[18:19], v[14:15], s[36:37] op_sel_hi:[1,0]
	s_nop 0
	v_cndmask_b32_e64 v20, 0, 32, vcc
	v_ldexp_f32 v1, v1, v20
	v_log_f32_e32 v1, v1
	s_nop 0
	v_mul_f32_e32 v20, 0x3f317217, v1
	v_fma_f32 v20, v1, s28, -v20
	v_fmac_f32_e32 v20, 0x3377d1cf, v1
	v_fmac_f32_e32 v20, 0x3f317217, v1
	v_cmp_lt_f32_e64 s[0:1], |v1|, s29
	s_nop 1
	v_cndmask_b32_e64 v1, v1, v20, s[0:1]
	v_cndmask_b32_e32 v20, 0, v244, vcc
	v_sub_f32_e32 v23, v1, v20
	v_mul_f32_e64 v1, |v16|, s94
	v_exp_f32_e32 v1, v1
	v_min_f32_e32 v20, 0, v16
	v_pk_add_f32 v[10:11], v[10:11], v[22:23] neg_lo:[0,1] neg_hi:[0,1]
	v_add_f32_e32 v1, 1.0, v1
	v_cmp_gt_f32_e32 vcc, s97, v1
	v_pk_mul_f32 v[22:23], v[10:11], s[36:37] op_sel_hi:[1,0]
	s_nop 0
	v_cndmask_b32_e64 v16, 0, 32, vcc
	v_ldexp_f32 v1, v1, v16
	v_log_f32_e32 v1, v1
	s_nop 0
	v_mul_f32_e32 v16, 0x3f317217, v1
	v_fma_f32 v16, v1, s28, -v16
	v_fmac_f32_e32 v16, 0x3377d1cf, v1
	v_fmac_f32_e32 v16, 0x3f317217, v1
	v_cmp_lt_f32_e64 s[0:1], |v1|, s29
	s_nop 1
	v_cndmask_b32_e64 v1, v1, v16, s[0:1]
	v_cndmask_b32_e32 v16, 0, v244, vcc
	v_sub_f32_e32 v16, v1, v16
	v_mul_f32_e64 v1, |v12|, s94
	v_exp_f32_e32 v1, v1
	s_nop 0
	v_add_f32_e32 v1, 1.0, v1
	v_cmp_gt_f32_e32 vcc, s97, v1
	s_nop 1
	v_cndmask_b32_e64 v12, 0, 32, vcc
	v_ldexp_f32 v1, v1, v12
	v_log_f32_e32 v1, v1
	s_nop 0
	v_mul_f32_e32 v12, 0x3f317217, v1
	v_fma_f32 v12, v1, s28, -v12
	v_fmac_f32_e32 v12, 0x3377d1cf, v1
	v_fmac_f32_e32 v12, 0x3f317217, v1
	v_cmp_lt_f32_e64 s[0:1], |v1|, s29
	s_nop 1
	v_cndmask_b32_e64 v1, v1, v12, s[0:1]
	v_cndmask_b32_e32 v12, 0, v244, vcc
	v_sub_f32_e32 v12, v1, v12
	v_mul_f32_e64 v1, |v17|, s94
	v_exp_f32_e32 v1, v1
	s_nop 0
	v_add_f32_e32 v1, 1.0, v1
	v_cmp_gt_f32_e32 vcc, s97, v1
	s_nop 1
	v_cndmask_b32_e64 v17, 0, 32, vcc
	v_ldexp_f32 v1, v1, v17
	v_log_f32_e32 v1, v1
	s_nop 0
	v_mul_f32_e32 v17, 0x3f317217, v1
	v_fma_f32 v17, v1, s28, -v17
	v_fmac_f32_e32 v17, 0x3377d1cf, v1
	v_fmac_f32_e32 v17, 0x3f317217, v1
	v_cmp_lt_f32_e64 s[0:1], |v1|, s29
	s_nop 1
	v_cndmask_b32_e64 v1, v1, v17, s[0:1]
	v_cndmask_b32_e32 v17, 0, v244, vcc
	v_sub_f32_e32 v17, v1, v17
	v_mul_f32_e64 v1, |v13|, s94
	v_exp_f32_e32 v1, v1
	v_pk_add_f32 v[16:17], v[20:21], v[16:17] neg_lo:[0,1] neg_hi:[0,1]
	v_add_f32_e32 v1, 1.0, v1
	v_cmp_gt_f32_e32 vcc, s97, v1
	v_pk_mul_f32 v[20:21], v[16:17], s[36:37] op_sel_hi:[1,0]
	s_nop 0
	v_cndmask_b32_e64 v13, 0, 32, vcc
	v_ldexp_f32 v1, v1, v13
	v_log_f32_e32 v1, v1
	s_nop 0
	v_mul_f32_e32 v13, 0x3f317217, v1
	v_fma_f32 v13, v1, s28, -v13
	v_fmac_f32_e32 v13, 0x3377d1cf, v1
	v_fmac_f32_e32 v13, 0x3f317217, v1
	v_cmp_lt_f32_e64 s[0:1], |v1|, s29
	s_nop 1
	v_cndmask_b32_e64 v1, v1, v13, s[0:1]
	v_cndmask_b32_e32 v13, 0, v244, vcc
	v_sub_f32_e32 v13, v1, v13
	v_pk_add_f32 v[12:13], v[24:25], v[12:13] neg_lo:[0,1] neg_hi:[0,1]
	s_nop 0
	v_pk_mul_f32 v[24:25], v[12:13], s[36:37] op_sel_hi:[1,0]

.LBB0_1254:
	s_andn2_b64 vcc, exec, s[0:1]
	s_cbranch_vccnz .LBB0_1256
	v_pk_add_f32 v[6:7], v[6:7], v[70:71]
	v_pk_add_f32 v[2:3], v[2:3], v[66:67]
	v_mul_f32_e64 v1, |v6|, s94
	v_exp_f32_e32 v1, v1
	v_mul_f32_e64 v12, |v7|, s94
	v_exp_f32_e32 v12, v12
	v_pk_add_f32 v[8:9], v[8:9], v[72:73]
	v_add_f32_e32 v1, 1.0, v1
	v_cmp_gt_f32_e32 vcc, s97, v1
	v_mul_f32_e64 v13, |v8|, s94
	v_exp_f32_e32 v13, v13
	v_cndmask_b32_e64 v10, 0, 32, vcc
	v_ldexp_f32 v1, v1, v10
	v_log_f32_e32 v1, v1
	v_mul_f32_e64 v10, |v2|, s94
	v_exp_f32_e32 v10, v10
	v_pk_add_f32 v[4:5], v[4:5], v[68:69]
	v_mul_f32_e32 v11, 0x3f317217, v1
	v_fma_f32 v11, v1, s28, -v11
	v_fmac_f32_e32 v11, 0x3377d1cf, v1
	v_fmac_f32_e32 v11, 0x3f317217, v1
	v_cmp_lt_f32_e64 s[0:1], |v1|, s29
	v_add_f32_e32 v10, 1.0, v10
	v_mul_f32_e64 v16, |v9|, s94
	v_cndmask_b32_e64 v1, v1, v11, s[0:1]
	v_cmp_gt_f32_e64 s[0:1], s97, v10
	v_exp_f32_e32 v16, v16
	v_mul_f32_e64 v17, |v5|, s94
	v_cndmask_b32_e64 v11, 0, 32, s[0:1]
	v_ldexp_f32 v10, v10, v11
	v_log_f32_e32 v11, v10
	v_cndmask_b32_e32 v10, 0, v244, vcc
	v_sub_f32_e32 v10, v1, v10
	v_exp_f32_e32 v17, v17
	v_mul_f32_e32 v1, 0x3f317217, v11
	v_fma_f32 v1, v11, s28, -v1
	v_fmac_f32_e32 v1, 0x3377d1cf, v11
	v_fmac_f32_e32 v1, 0x3f317217, v11
	v_cmp_lt_f32_e64 vcc, |v11|, s29
	v_min_f32_e32 v6, 0, v6
	v_min_f32_e32 v7, 0, v7
	v_cndmask_b32_e32 v1, v11, v1, vcc
	v_add_f32_e32 v11, 1.0, v12
	v_cmp_gt_f32_e32 vcc, s97, v11
	v_min_f32_e32 v2, 0, v2
	v_min_f32_e32 v8, 0, v8
	v_cndmask_b32_e64 v12, 0, 32, vcc
	v_ldexp_f32 v11, v11, v12
	v_log_f32_e32 v11, v11
	v_cndmask_b32_e64 v12, 0, v244, s[0:1]
	v_sub_f32_e32 v14, v1, v12
	v_mul_f32_e64 v12, |v3|, s94
	v_mul_f32_e32 v1, 0x3f317217, v11
	v_exp_f32_e32 v12, v12
	v_fma_f32 v1, v11, s28, -v1
	v_fmac_f32_e32 v1, 0x3377d1cf, v11
	v_fmac_f32_e32 v1, 0x3f317217, v11
	v_cmp_lt_f32_e64 s[0:1], |v11|, s29
	v_min_f32_e32 v3, 0, v3
	v_min_f32_e32 v9, 0, v9
	v_cndmask_b32_e64 v1, v11, v1, s[0:1]
	v_add_f32_e32 v11, 1.0, v12
	v_cmp_gt_f32_e64 s[0:1], s97, v11
	v_min_f32_e32 v5, 0, v5
	s_nop 0
	v_cndmask_b32_e64 v12, 0, 32, s[0:1]
	v_ldexp_f32 v11, v11, v12
	v_log_f32_e32 v12, v11
	v_cndmask_b32_e32 v11, 0, v244, vcc
	v_sub_f32_e32 v11, v1, v11
	v_pk_add_f32 v[6:7], v[6:7], v[10:11] neg_lo:[0,1] neg_hi:[0,1]
	v_mul_f32_e32 v1, 0x3f317217, v12
	v_fma_f32 v1, v12, s28, -v1
	v_fmac_f32_e32 v1, 0x3377d1cf, v12
	v_fmac_f32_e32 v1, 0x3f317217, v12
	v_cmp_lt_f32_e64 vcc, |v12|, s29
	s_nop 1
	v_cndmask_b32_e32 v1, v12, v1, vcc
	v_add_f32_e32 v12, 1.0, v13
	v_cmp_gt_f32_e32 vcc, s97, v12
	s_nop 1
	v_cndmask_b32_e64 v13, 0, 32, vcc
	v_ldexp_f32 v12, v12, v13
	v_log_f32_e32 v12, v12
	v_cndmask_b32_e64 v13, 0, v244, s[0:1]
	v_sub_f32_e32 v15, v1, v13
	v_mul_f32_e64 v13, |v4|, s94
	v_mul_f32_e32 v1, 0x3f317217, v12
	v_exp_f32_e32 v13, v13
	v_fma_f32 v1, v12, s28, -v1
	v_fmac_f32_e32 v1, 0x3377d1cf, v12
	v_fmac_f32_e32 v1, 0x3f317217, v12
	v_cmp_lt_f32_e64 s[0:1], |v12|, s29
	v_min_f32_e32 v4, 0, v4
	v_pk_add_f32 v[2:3], v[2:3], v[14:15] neg_lo:[0,1] neg_hi:[0,1]
	v_cndmask_b32_e64 v1, v12, v1, s[0:1]
	v_add_f32_e32 v12, 1.0, v13
	v_cmp_gt_f32_e64 s[0:1], s97, v12
	v_pk_mul_f32 v[14:15], v[2:3], s[36:37] op_sel_hi:[1,0]
	s_nop 0
	v_cndmask_b32_e64 v13, 0, 32, s[0:1]
	v_ldexp_f32 v12, v12, v13
	v_log_f32_e32 v13, v12
	v_cndmask_b32_e32 v12, 0, v244, vcc
	v_sub_f32_e32 v12, v1, v12
	v_mul_f32_e32 v1, 0x3f317217, v13
	v_fma_f32 v1, v13, s28, -v1
	v_fmac_f32_e32 v1, 0x3377d1cf, v13
	v_fmac_f32_e32 v1, 0x3f317217, v13
	v_cmp_lt_f32_e64 vcc, |v13|, s29
	s_nop 1
	v_cndmask_b32_e32 v1, v13, v1, vcc
	v_add_f32_e32 v13, 1.0, v16
	v_cmp_gt_f32_e32 vcc, s97, v13
	s_nop 1
	v_cndmask_b32_e64 v16, 0, 32, vcc
	v_ldexp_f32 v13, v13, v16
	v_log_f32_e32 v13, v13
	v_cndmask_b32_e64 v16, 0, v244, s[0:1]
	v_sub_f32_e32 v16, v1, v16
	v_mul_f32_e32 v1, 0x3f317217, v13
	v_fma_f32 v1, v13, s28, -v1
	v_fmac_f32_e32 v1, 0x3377d1cf, v13
	v_fmac_f32_e32 v1, 0x3f317217, v13
	v_cmp_lt_f32_e64 s[0:1], |v13|, s29
	s_nop 1
	v_cndmask_b32_e64 v1, v13, v1, s[0:1]
	v_cndmask_b32_e32 v13, 0, v244, vcc
	v_sub_f32_e32 v13, v1, v13
	v_add_f32_e32 v1, 1.0, v17
	v_cmp_gt_f32_e32 vcc, s97, v1
	v_pk_add_f32 v[8:9], v[8:9], v[12:13] neg_lo:[0,1] neg_hi:[0,1]
	s_nop 0
	v_cndmask_b32_e64 v10, 0, 32, vcc
	v_ldexp_f32 v1, v1, v10
	v_log_f32_e32 v1, v1
	v_pk_mul_f32 v[10:11], v[6:7], s[36:37] op_sel_hi:[1,0]
	v_pk_mul_f32 v[12:13], v[8:9], s[36:37] op_sel_hi:[1,0]
	v_mul_f32_e32 v6, 0x3f317217, v1
	v_fma_f32 v6, v1, s28, -v6
	v_fmac_f32_e32 v6, 0x3377d1cf, v1
	v_fmac_f32_e32 v6, 0x3f317217, v1
	v_cmp_lt_f32_e64 s[0:1], |v1|, s29
	s_nop 1
	v_cndmask_b32_e64 v1, v1, v6, s[0:1]
	v_cndmask_b32_e32 v6, 0, v244, vcc
	v_sub_f32_e32 v17, v1, v6
	v_pk_add_f32 v[4:5], v[4:5], v[16:17] neg_lo:[0,1] neg_hi:[0,1]
	s_nop 0
	v_pk_mul_f32 v[16:17], v[4:5], s[36:37] op_sel_hi:[1,0]

.LBB0_1455:
	s_and_b64 vcc, exec, s[0:1]
	s_mov_b64 s[16:17], s[20:21]
	s_cbranch_vccnz .LBB0_1457
	s_ashr_i32 s16, s69, 31
	s_mul_hi_u32 s17, s6, s69
	s_mul_i32 s16, s6, s16
	s_add_i32 s16, s17, s16
	s_mul_i32 s17, s7, s69
	s_add_i32 s17, s16, s17
	s_mul_i32 s16, s6, s69
	v_readlane_b32 s31, v253, 51
	s_add_u32 s16, s31, s16
	v_readlane_b32 s31, v253, 52
	s_addc_u32 s17, s31, s17
.LBB0_1457:
	s_andn2_b64 vcc, exec, s[12:13]
	s_cbranch_vccz .Lzgo_6
	v_mov_b32_e32 v129, 0
	v_mov_b32_e32 v128, v129
	v_mov_b32_e32 v127, v129
	v_mov_b32_e32 v126, v129
	v_mov_b32_e32 v97, v129
	v_mov_b32_e32 v96, v129
	v_mov_b32_e32 v95, v129
	v_mov_b32_e32 v94, v129
	v_mov_b32_e32 v125, v129
	v_mov_b32_e32 v124, v129
	v_mov_b32_e32 v123, v129
	v_mov_b32_e32 v122, v129
	v_mov_b32_e32 v93, v129
	v_mov_b32_e32 v92, v129
	v_mov_b32_e32 v91, v129
	v_mov_b32_e32 v90, v129
	v_mov_b32_e32 v121, v129
	v_mov_b32_e32 v120, v129
	v_mov_b32_e32 v119, v129
	v_mov_b32_e32 v118, v129
	v_mov_b32_e32 v89, v129
	v_mov_b32_e32 v88, v129
	v_mov_b32_e32 v87, v129
	v_mov_b32_e32 v86, v129
	v_mov_b32_e32 v117, v129
	v_mov_b32_e32 v116, v129
	v_mov_b32_e32 v115, v129
	v_mov_b32_e32 v114, v129
	v_mov_b32_e32 v85, v129
	v_mov_b32_e32 v84, v129
	v_mov_b32_e32 v83, v129
	v_mov_b32_e32 v82, v129
	v_mov_b32_e32 v65, v129
	v_mov_b32_e32 v64, v129
	v_mov_b32_e32 v63, v129
	v_mov_b32_e32 v62, v129
	v_mov_b32_e32 v33, v129
	v_mov_b32_e32 v32, v129
	v_mov_b32_e32 v31, v129
	v_mov_b32_e32 v30, v129
	v_mov_b32_e32 v61, v129
	v_mov_b32_e32 v60, v129
	v_mov_b32_e32 v59, v129
	v_mov_b32_e32 v58, v129
	v_mov_b32_e32 v29, v129
	v_mov_b32_e32 v28, v129
	v_mov_b32_e32 v27, v129
	v_mov_b32_e32 v26, v129
	v_mov_b32_e32 v57, v129
	v_mov_b32_e32 v56, v129
	v_mov_b32_e32 v55, v129
	v_mov_b32_e32 v54, v129
	v_mov_b32_e32 v25, v129
	v_mov_b32_e32 v24, v129
	v_mov_b32_e32 v23, v129
	v_mov_b32_e32 v22, v129
	v_mov_b32_e32 v53, v129
	v_mov_b32_e32 v52, v129
	v_mov_b32_e32 v51, v129
	v_mov_b32_e32 v50, v129
	v_mov_b32_e32 v21, v129
	v_mov_b32_e32 v20, v129
	v_mov_b32_e32 v19, v129
	v_mov_b32_e32 v18, v129
	v_mov_b32_e32 v113, v129
	v_mov_b32_e32 v112, v129
	v_mov_b32_e32 v111, v129
	v_mov_b32_e32 v110, v129
	v_mov_b32_e32 v81, v129
	v_mov_b32_e32 v80, v129
	v_mov_b32_e32 v79, v129
	v_mov_b32_e32 v78, v129
	v_mov_b32_e32 v109, v129
	v_mov_b32_e32 v108, v129
	v_mov_b32_e32 v107, v129
	v_mov_b32_e32 v106, v129
	v_mov_b32_e32 v77, v129
	v_mov_b32_e32 v76, v129
	v_mov_b32_e32 v75, v129
	v_mov_b32_e32 v74, v129
	v_mov_b32_e32 v105, v129
	v_mov_b32_e32 v104, v129
	v_mov_b32_e32 v103, v129
	v_mov_b32_e32 v102, v129
	v_mov_b32_e32 v73, v129
	v_mov_b32_e32 v72, v129
	v_mov_b32_e32 v71, v129
	v_mov_b32_e32 v70, v129
	v_mov_b32_e32 v101, v129
	v_mov_b32_e32 v100, v129
	v_mov_b32_e32 v99, v129
	v_mov_b32_e32 v98, v129
	v_mov_b32_e32 v69, v129
	v_mov_b32_e32 v68, v129
	v_mov_b32_e32 v67, v129
	v_mov_b32_e32 v66, v129
	v_mov_b32_e32 v49, v129
	v_mov_b32_e32 v48, v129
	v_mov_b32_e32 v47, v129
	v_mov_b32_e32 v46, v129
	v_mov_b32_e32 v17, v129
	v_mov_b32_e32 v16, v129
	v_mov_b32_e32 v15, v129
	v_mov_b32_e32 v14, v129
	v_mov_b32_e32 v45, v129
	v_mov_b32_e32 v44, v129
	v_mov_b32_e32 v43, v129
	v_mov_b32_e32 v42, v129
	v_mov_b32_e32 v13, v129
	v_mov_b32_e32 v12, v129
	v_mov_b32_e32 v11, v129
	v_mov_b32_e32 v10, v129
	v_mov_b32_e32 v41, v129
	v_mov_b32_e32 v40, v129
	v_mov_b32_e32 v39, v129
	v_mov_b32_e32 v38, v129
	v_mov_b32_e32 v9, v129
	v_mov_b32_e32 v8, v129
	v_mov_b32_e32 v7, v129
	v_mov_b32_e32 v6, v129
	v_mov_b32_e32 v37, v129
	v_mov_b32_e32 v36, v129
	v_mov_b32_e32 v35, v129
	v_mov_b32_e32 v34, v129
	v_mov_b32_e32 v5, v129
	v_mov_b32_e32 v4, v129
	v_mov_b32_e32 v3, v129
	v_mov_b32_e32 v2, v129
	s_branch .LBB0_1460
